# v85 + lora2 item order: 8 waves of a workgroup share one channel half
# baseline (speedup 1.0000x reference)
.LBB0_453:
	s_sub_i32 s2, s54, s56
	s_lshr_b32 s2, s2, 3
	s_add_i32 s2, s2, s56
	s_cmp_lt_i32 s54, s56
	s_cselect_b32 s24, s54, s2
	s_cselect_b32 s10, 0, s58
	s_cselect_b32 s60, 8, s59
	s_cbranch_scc0 .Llora_noremap
	s_and_b32 s2, s24, 7
	s_lshl_b32 s2, s2, 1
	s_bfe_u32 s4, s24, 0x10003
	s_or_b32 s2, s2, s4
	s_and_b32 s24, s24, -16
	s_or_b32 s24, s24, s2
.Llora_noremap:
	s_lshl_b32 s2, s24, 3
	v_and_or_b32 v56, s2, -16, v226
	v_cmp_gt_i32_e32 vcc, s71, v56
	v_mov_b32_e32 v0, 0xff
	v_mov_b32_e32 v1, 0x1fff
	v_cndmask_b32_e32 v0, v0, v1, vcc
	v_and_b32_e32 v1, v0, v56
	v_cmp_eq_u32_e64 s[38:39], 0, v1
	v_cmp_eq_u32_e64 s[36:37], v1, v0
	v_mov_b64_e32 v[0:1], s[40:41]
	v_mad_i64_i32 v[0:1], s[4:5], v56, s17, v[0:1]
	v_mov_b32_e32 v2, 0xffffd200
	v_cndmask_b32_e64 v3, -1, 0, s[38:39]
	v_cndmask_b32_e64 v2, v2, 0, s[38:39]
	v_lshl_add_u64 v[34:35], v[0:1], 0, v[166:167]
	v_lshl_add_u64 v[8:9], v[0:1], 0, v[2:3]
	v_mov_b32_e32 v2, 0x2e00
	v_add_co_u32_e32 v36, vcc, s79, v34
	v_cndmask_b32_e64 v208, v2, 0, s[36:37]
	s_nop 0
	v_addc_co_u32_e32 v37, vcc, 0, v35, vcc
	v_lshl_add_u64 v[32:33], v[0:1], 0, v[208:209]
	global_load_dwordx4 v[0:3], v[36:37], off offset:2560
	v_lshl_add_u64 v[40:41], v[8:9], 0, v[166:167]
	v_add_co_u32_e32 v38, vcc, s79, v40
	s_mov_b64 s[8:9], 0x2a00
	s_nop 0
	v_addc_co_u32_e32 v39, vcc, 0, v41, vcc
	v_lshl_add_u64 v[24:25], v[34:35], 0, s[8:9]
	v_lshl_add_u64 v[8:9], v[40:41], 0, s[8:9]
	s_mov_b64 s[12:13], 0x2b00
	v_lshl_add_u64 v[28:29], v[34:35], 0, s[12:13]
	s_lshl_b32 s2, s24, 9
	s_and_b32 s2, s2, 0x200
	v_ashrrev_i32_e32 v57, 31, v56
	v_mov_b32_e32 v197, v209
	s_waitcnt vmcnt(0)
	v_lshlrev_b32_e32 v18, 16, v0
	v_and_b32_e32 v19, 0xffff0000, v0
	v_lshlrev_b32_e32 v20, 16, v1
	v_and_b32_e32 v21, 0xffff0000, v1
	v_lshlrev_b32_e32 v4, 16, v2
	v_and_b32_e32 v5, 0xffff0000, v2
	v_lshlrev_b32_e32 v6, 16, v3
	v_and_b32_e32 v7, 0xffff0000, v3
	global_load_dwordx4 v[0:3], v[38:39], off offset:2560
	s_waitcnt vmcnt(0)
	v_cndmask_b32_e64 v3, v3, 0, s[38:39]
	v_cndmask_b32_e64 v2, v2, 0, s[38:39]
	v_cndmask_b32_e64 v1, v1, 0, s[38:39]
	v_cndmask_b32_e64 v0, v0, 0, s[38:39]
	v_lshlrev_b32_e32 v22, 16, v0
	v_and_b32_e32 v23, 0xffff0000, v0
	v_lshlrev_b32_e32 v26, 16, v1
	v_and_b32_e32 v27, 0xffff0000, v1
	v_lshlrev_b32_e32 v14, 16, v2
	v_and_b32_e32 v16, 0xffff0000, v2
	v_lshlrev_b32_e32 v15, 16, v3
	v_and_b32_e32 v17, 0xffff0000, v3
	global_load_dwordx4 v[0:3], v[172:173], off offset:16
	global_load_dwordx4 v[10:13], v[172:173], off
	v_sub_f32_e32 v23, v23, v19
	v_sub_f32_e32 v22, v22, v18
	v_sub_f32_e32 v27, v27, v21
	v_sub_f32_e32 v26, v26, v20
	v_sub_f32_e32 v17, v17, v7
	s_waitcnt vmcnt(0)
	v_pk_fma_f32 v[10:11], v[10:11], v[22:23], v[18:19]
	s_nop 0
	v_add_f32_e32 v10, v10, v10
	v_add_f32_e32 v11, v11, v11
	v_mul_f32_e32 v10, 0x3fb8aa3b, v10
	v_mul_f32_e32 v11, 0x3fb8aa3b, v11
	v_exp_f32_e32 v10, v10
	v_exp_f32_e32 v11, v11
	v_pk_fma_f32 v[12:13], v[12:13], v[26:27], v[20:21]
	v_pk_add_f32 v[10:11], v[10:11], 1.0 op_sel_hi:[1,0]
	s_nop 0
	v_div_scale_f32 v18, s[4:5], v11, v11, 2.0
	v_rcp_f32_e32 v19, v18
	v_add_f32_e32 v12, v12, v12
	v_add_f32_e32 v13, v13, v13
	v_mul_f32_e32 v12, 0x3fb8aa3b, v12
	v_fma_f32 v20, -v18, v19, 1.0
	v_fmac_f32_e32 v19, v20, v19
	v_div_scale_f32 v20, vcc, 2.0, v11, 2.0
	v_mul_f32_e32 v21, v20, v19
	v_fma_f32 v22, -v18, v21, v20
	v_fmac_f32_e32 v21, v22, v19
	v_fma_f32 v18, -v18, v21, v20
	v_div_fmas_f32 v18, v18, v19, v21
	v_div_fixup_f32 v11, v18, v11, 2.0
	v_div_scale_f32 v18, s[4:5], v10, v10, 2.0
	v_rcp_f32_e32 v19, v18
	v_mul_f32_e32 v13, 0x3fb8aa3b, v13
	v_exp_f32_e32 v12, v12
	v_exp_f32_e32 v13, v13
	v_fma_f32 v20, -v18, v19, 1.0
	v_fmac_f32_e32 v19, v20, v19
	v_div_scale_f32 v20, vcc, 2.0, v10, 2.0
	v_mul_f32_e32 v21, v20, v19
	v_fma_f32 v22, -v18, v21, v20
	v_fmac_f32_e32 v21, v22, v19
	v_fma_f32 v18, -v18, v21, v20
	v_div_fmas_f32 v18, v18, v19, v21
	v_pk_add_f32 v[12:13], v[12:13], 1.0 op_sel_hi:[1,0]
	v_div_fixup_f32 v10, v18, v10, 2.0
	v_div_scale_f32 v18, s[4:5], v13, v13, 2.0
	v_rcp_f32_e32 v19, v18
	v_pk_add_f32 v[10:11], v[10:11], 1.0 op_sel_hi:[1,0] neg_lo:[1,0] neg_hi:[1,0]
	v_fma_f32 v20, -v18, v19, 1.0
	v_fmac_f32_e32 v19, v20, v19
	v_div_scale_f32 v20, vcc, 2.0, v13, 2.0
	v_mul_f32_e32 v21, v20, v19
	v_fma_f32 v22, -v18, v21, v20
	v_fmac_f32_e32 v21, v22, v19
	v_fma_f32 v18, -v18, v21, v20
	v_div_fmas_f32 v18, v18, v19, v21
	v_div_fixup_f32 v13, v18, v13, 2.0
	v_div_scale_f32 v18, s[4:5], v12, v12, 2.0
	v_rcp_f32_e32 v19, v18
	s_nop 0
	v_fma_f32 v20, -v18, v19, 1.0
	v_fmac_f32_e32 v19, v20, v19
	v_div_scale_f32 v20, vcc, 2.0, v12, 2.0
	v_mul_f32_e32 v21, v20, v19
	v_fma_f32 v22, -v18, v21, v20
	v_fmac_f32_e32 v21, v22, v19
	v_fma_f32 v18, -v18, v21, v20
	v_div_fmas_f32 v18, v18, v19, v21
	v_div_fixup_f32 v12, v18, v12, 2.0
	v_sub_f32_e32 v19, v16, v5
	v_sub_f32_e32 v18, v14, v4
	v_pk_fma_f32 v[0:1], v[0:1], v[18:19], v[4:5]
	v_sub_f32_e32 v16, v15, v6
	v_add_f32_e32 v0, v0, v0
	v_add_f32_e32 v1, v1, v1
	v_mul_f32_e32 v0, 0x3fb8aa3b, v0
	v_mul_f32_e32 v1, 0x3fb8aa3b, v1
	v_exp_f32_e32 v0, v0
	v_exp_f32_e32 v1, v1
	v_pk_fma_f32 v[2:3], v[2:3], v[16:17], v[6:7]
	v_pk_add_f32 v[12:13], v[12:13], 1.0 op_sel_hi:[1,0] neg_lo:[1,0] neg_hi:[1,0]
	v_pk_add_f32 v[0:1], v[0:1], 1.0 op_sel_hi:[1,0]
	s_nop 0
	v_div_scale_f32 v4, s[4:5], v1, v1, 2.0
	v_rcp_f32_e32 v5, v4
	s_nop 0
	v_fma_f32 v6, -v4, v5, 1.0
	v_fmac_f32_e32 v5, v6, v5
	v_div_scale_f32 v6, vcc, 2.0, v1, 2.0
	v_mul_f32_e32 v7, v6, v5
	v_fma_f32 v14, -v4, v7, v6
	v_fmac_f32_e32 v7, v14, v5
	v_fma_f32 v4, -v4, v7, v6
	v_div_fmas_f32 v4, v4, v5, v7
	v_div_fixup_f32 v1, v4, v1, 2.0
	v_div_scale_f32 v4, s[4:5], v0, v0, 2.0
	v_rcp_f32_e32 v5, v4
	s_nop 0
	v_fma_f32 v6, -v4, v5, 1.0
	v_fmac_f32_e32 v5, v6, v5
	v_div_scale_f32 v6, vcc, 2.0, v0, 2.0
	v_mul_f32_e32 v7, v6, v5
	v_fma_f32 v14, -v4, v7, v6
	v_fmac_f32_e32 v7, v14, v5
	v_fma_f32 v4, -v4, v7, v6
	v_div_fmas_f32 v4, v4, v5, v7
	v_div_fixup_f32 v0, v4, v0, 2.0
	v_pk_add_f32 v[4:5], v[0:1], 1.0 op_sel_hi:[1,0] neg_lo:[1,0] neg_hi:[1,0]
	v_add_f32_e32 v0, v2, v2
	v_add_f32_e32 v1, v3, v3
	v_mul_f32_e32 v0, 0x3fb8aa3b, v0
	v_mul_f32_e32 v1, 0x3fb8aa3b, v1
	v_exp_f32_e32 v0, v0
	v_exp_f32_e32 v1, v1
	s_nop 0
	v_pk_add_f32 v[0:1], v[0:1], 1.0 op_sel_hi:[1,0]
	s_nop 0
	v_div_scale_f32 v2, s[4:5], v1, v1, 2.0
	v_rcp_f32_e32 v3, v2
	s_nop 0
	v_fma_f32 v6, -v2, v3, 1.0
	v_fmac_f32_e32 v3, v6, v3
	v_div_scale_f32 v6, vcc, 2.0, v1, 2.0
	v_mul_f32_e32 v7, v6, v3
	v_fma_f32 v14, -v2, v7, v6
	v_fmac_f32_e32 v7, v14, v3
	v_fma_f32 v2, -v2, v7, v6
	v_div_fmas_f32 v2, v2, v3, v7
	v_div_fixup_f32 v1, v2, v1, 2.0
	v_div_scale_f32 v2, s[4:5], v0, v0, 2.0
	v_rcp_f32_e32 v3, v2
	s_nop 0
	v_fma_f32 v6, -v2, v3, 1.0
	v_fmac_f32_e32 v3, v6, v3
	v_div_scale_f32 v6, vcc, 2.0, v0, 2.0
	v_mul_f32_e32 v7, v6, v3
	v_fma_f32 v14, -v2, v7, v6
	v_fmac_f32_e32 v7, v14, v3
	v_fma_f32 v2, -v2, v7, v6
	v_div_fmas_f32 v2, v2, v3, v7
	v_div_fixup_f32 v0, v2, v0, 2.0
	v_pk_add_f32 v[6:7], v[0:1], 1.0 op_sel_hi:[1,0] neg_lo:[1,0] neg_hi:[1,0]
	v_cvt_pk_bf16_f32 v0, v10, v11
	v_cvt_pk_bf16_f32 v1, v12, v13
	v_cvt_pk_bf16_f32 v2, v4, v5
	v_cvt_pk_bf16_f32 v3, v6, v7
	global_load_dwordx4 v[4:7], v[36:37], off offset:2816
	v_lshl_add_u64 v[12:13], v[40:41], 0, s[12:13]
	s_waitcnt vmcnt(0)
	v_lshlrev_b32_e32 v10, 16, v4
	v_and_b32_e32 v11, 0xffff0000, v4
	v_lshlrev_b32_e32 v18, 16, v5
	v_and_b32_e32 v19, 0xffff0000, v5
	v_lshlrev_b32_e32 v20, 16, v6
	v_and_b32_e32 v21, 0xffff0000, v6
	v_lshlrev_b32_e32 v22, 16, v7
	v_and_b32_e32 v23, 0xffff0000, v7
	global_load_dwordx4 v[4:7], v[38:39], off offset:2816
	s_waitcnt vmcnt(0)
	v_cndmask_b32_e64 v7, v7, 0, s[38:39]
	v_cndmask_b32_e64 v6, v6, 0, s[38:39]
	v_cndmask_b32_e64 v5, v5, 0, s[38:39]
	v_cndmask_b32_e64 v4, v4, 0, s[38:39]
	v_lshlrev_b32_e32 v26, 16, v4
	v_and_b32_e32 v27, 0xffff0000, v4
	v_lshlrev_b32_e32 v30, 16, v5
	v_and_b32_e32 v31, 0xffff0000, v5
	v_lshlrev_b32_e32 v42, 16, v6
	v_and_b32_e32 v43, 0xffff0000, v6
	v_lshlrev_b32_e32 v44, 16, v7
	v_and_b32_e32 v45, 0xffff0000, v7
	global_load_dwordx4 v[4:7], v[174:175], off offset:16
	global_load_dwordx4 v[14:17], v[174:175], off
	v_sub_f32_e32 v27, v27, v11
	v_sub_f32_e32 v26, v26, v10
	v_sub_f32_e32 v31, v31, v19
	v_sub_f32_e32 v30, v30, v18
	s_waitcnt vmcnt(0)
	v_pk_fma_f32 v[16:17], v[16:17], v[30:31], v[18:19]
	v_pk_fma_f32 v[10:11], v[14:15], v[26:27], v[10:11]
	v_sub_f32_e32 v15, v43, v21
	v_sub_f32_e32 v14, v42, v20
	v_sub_f32_e32 v19, v45, v23
	v_sub_f32_e32 v18, v44, v22
	v_pk_fma_f32 v[18:19], v[6:7], v[18:19], v[22:23]
	v_pk_fma_f32 v[6:7], v[4:5], v[14:15], v[20:21]
	v_cvt_pk_bf16_f32 v4, v10, v11
	v_cvt_pk_bf16_f32 v5, v16, v17
	v_cvt_pk_bf16_f32 v6, v6, v7
	v_cvt_pk_bf16_f32 v7, v18, v19
	global_load_dwordx4 v[14:17], v[24:25], off offset:64
	s_nop 0
	global_load_dwordx4 v[8:11], v[8:9], off offset:64
	s_waitcnt vmcnt(1)
	v_lshlrev_b32_e32 v26, 16, v14
	v_and_b32_e32 v27, 0xffff0000, v14
	s_waitcnt vmcnt(0)
	v_cndmask_b32_e64 v11, v11, 0, s[38:39]
	v_cndmask_b32_e64 v10, v10, 0, s[38:39]
	v_cndmask_b32_e64 v9, v9, 0, s[38:39]
	v_cndmask_b32_e64 v8, v8, 0, s[38:39]
	v_lshlrev_b32_e32 v42, 16, v8
	v_and_b32_e32 v43, 0xffff0000, v8
	v_lshlrev_b32_e32 v44, 16, v9
	v_and_b32_e32 v45, 0xffff0000, v9
	v_lshlrev_b32_e32 v22, 16, v10
	v_and_b32_e32 v46, 0xffff0000, v10
	v_lshlrev_b32_e32 v23, 16, v11
	v_and_b32_e32 v47, 0xffff0000, v11
	global_load_dwordx4 v[8:11], v[172:173], off offset:144
	global_load_dwordx4 v[18:21], v[172:173], off offset:128
	v_sub_f32_e32 v43, v43, v27
	v_sub_f32_e32 v42, v42, v26
	v_lshlrev_b32_e32 v30, 16, v15
	v_and_b32_e32 v31, 0xffff0000, v15
	v_sub_f32_e32 v45, v45, v31
	v_sub_f32_e32 v44, v44, v30
	v_lshlrev_b32_e32 v14, 16, v16
	v_and_b32_e32 v15, 0xffff0000, v16
	v_lshlrev_b32_e32 v16, 16, v17
	v_and_b32_e32 v17, 0xffff0000, v17
	s_waitcnt vmcnt(0)
	v_pk_fma_f32 v[18:19], v[18:19], v[42:43], v[26:27]
	s_nop 0
	v_add_f32_e32 v18, v18, v18
	v_add_f32_e32 v19, v19, v19
	v_mul_f32_e32 v18, 0x3fb8aa3b, v18
	v_mul_f32_e32 v19, 0x3fb8aa3b, v19
	v_exp_f32_e32 v18, v18
	v_exp_f32_e32 v19, v19
	v_pk_fma_f32 v[20:21], v[20:21], v[44:45], v[30:31]
	v_pk_add_f32 v[18:19], v[18:19], 1.0 op_sel_hi:[1,0]
	s_nop 0
	v_div_scale_f32 v26, s[4:5], v19, v19, 2.0
	v_rcp_f32_e32 v27, v26
	v_add_f32_e32 v20, v20, v20
	v_add_f32_e32 v21, v21, v21
	v_mul_f32_e32 v20, 0x3fb8aa3b, v20
	v_fma_f32 v30, -v26, v27, 1.0
	v_fmac_f32_e32 v27, v30, v27
	v_div_scale_f32 v30, vcc, 2.0, v19, 2.0
	v_mul_f32_e32 v31, v30, v27
	v_fma_f32 v42, -v26, v31, v30
	v_fmac_f32_e32 v31, v42, v27
	v_fma_f32 v26, -v26, v31, v30
	v_div_fmas_f32 v26, v26, v27, v31
	v_div_fixup_f32 v19, v26, v19, 2.0
	v_div_scale_f32 v26, s[4:5], v18, v18, 2.0
	v_rcp_f32_e32 v27, v26
	v_mul_f32_e32 v21, 0x3fb8aa3b, v21
	v_exp_f32_e32 v20, v20
	v_exp_f32_e32 v21, v21
	v_fma_f32 v30, -v26, v27, 1.0
	v_fmac_f32_e32 v27, v30, v27
	v_div_scale_f32 v30, vcc, 2.0, v18, 2.0
	v_mul_f32_e32 v31, v30, v27
	v_fma_f32 v42, -v26, v31, v30
	v_fmac_f32_e32 v31, v42, v27
	v_fma_f32 v26, -v26, v31, v30
	v_div_fmas_f32 v26, v26, v27, v31
	v_pk_add_f32 v[20:21], v[20:21], 1.0 op_sel_hi:[1,0]
	v_div_fixup_f32 v18, v26, v18, 2.0
	v_div_scale_f32 v26, s[4:5], v21, v21, 2.0
	v_rcp_f32_e32 v27, v26
	v_pk_add_f32 v[18:19], v[18:19], 1.0 op_sel_hi:[1,0] neg_lo:[1,0] neg_hi:[1,0]
	v_fma_f32 v30, -v26, v27, 1.0
	v_fmac_f32_e32 v27, v30, v27
	v_div_scale_f32 v30, vcc, 2.0, v21, 2.0
	v_mul_f32_e32 v31, v30, v27
	v_fma_f32 v42, -v26, v31, v30
	v_fmac_f32_e32 v31, v42, v27
	v_fma_f32 v26, -v26, v31, v30
	v_div_fmas_f32 v26, v26, v27, v31
	v_div_fixup_f32 v21, v26, v21, 2.0
	v_div_scale_f32 v26, s[4:5], v20, v20, 2.0
	v_rcp_f32_e32 v27, v26
	s_nop 0
	v_fma_f32 v30, -v26, v27, 1.0
	v_fmac_f32_e32 v27, v30, v27
	v_div_scale_f32 v30, vcc, 2.0, v20, 2.0
	v_mul_f32_e32 v31, v30, v27
	v_fma_f32 v42, -v26, v31, v30
	v_fmac_f32_e32 v31, v42, v27
	v_fma_f32 v26, -v26, v31, v30
	v_div_fmas_f32 v26, v26, v27, v31
	v_div_fixup_f32 v20, v26, v20, 2.0
	v_sub_f32_e32 v27, v46, v15
	v_sub_f32_e32 v26, v22, v14
	v_pk_fma_f32 v[8:9], v[8:9], v[26:27], v[14:15]
	v_sub_f32_e32 v31, v47, v17
	v_add_f32_e32 v8, v8, v8
	v_add_f32_e32 v9, v9, v9
	v_mul_f32_e32 v8, 0x3fb8aa3b, v8
	v_mul_f32_e32 v9, 0x3fb8aa3b, v9
	v_exp_f32_e32 v8, v8
	v_exp_f32_e32 v9, v9
	v_sub_f32_e32 v30, v23, v16
	v_pk_fma_f32 v[10:11], v[10:11], v[30:31], v[16:17]
	v_pk_add_f32 v[20:21], v[20:21], 1.0 op_sel_hi:[1,0] neg_lo:[1,0] neg_hi:[1,0]
	v_pk_add_f32 v[8:9], v[8:9], 1.0 op_sel_hi:[1,0]
	s_nop 0
	v_div_scale_f32 v14, s[4:5], v9, v9, 2.0
	v_rcp_f32_e32 v15, v14
	s_nop 0
	v_fma_f32 v16, -v14, v15, 1.0
	v_fmac_f32_e32 v15, v16, v15
	v_div_scale_f32 v16, vcc, 2.0, v9, 2.0
	v_mul_f32_e32 v17, v16, v15
	v_fma_f32 v22, -v14, v17, v16
	v_fmac_f32_e32 v17, v22, v15
	v_fma_f32 v14, -v14, v17, v16
	v_div_fmas_f32 v14, v14, v15, v17
	v_div_fixup_f32 v9, v14, v9, 2.0
	v_div_scale_f32 v14, s[4:5], v8, v8, 2.0
	v_rcp_f32_e32 v15, v14
	s_nop 0
	v_fma_f32 v16, -v14, v15, 1.0
	v_fmac_f32_e32 v15, v16, v15
	v_div_scale_f32 v16, vcc, 2.0, v8, 2.0
	v_mul_f32_e32 v17, v16, v15
	v_fma_f32 v22, -v14, v17, v16
	v_fmac_f32_e32 v17, v22, v15
	v_fma_f32 v14, -v14, v17, v16
	v_div_fmas_f32 v14, v14, v15, v17
	v_div_fixup_f32 v8, v14, v8, 2.0
	v_pk_add_f32 v[14:15], v[8:9], 1.0 op_sel_hi:[1,0] neg_lo:[1,0] neg_hi:[1,0]
	v_add_f32_e32 v8, v10, v10
	v_add_f32_e32 v9, v11, v11
	v_mul_f32_e32 v8, 0x3fb8aa3b, v8
	v_mul_f32_e32 v9, 0x3fb8aa3b, v9
	v_exp_f32_e32 v8, v8
	v_exp_f32_e32 v9, v9
	s_nop 0
	v_pk_add_f32 v[8:9], v[8:9], 1.0 op_sel_hi:[1,0]
	s_nop 0
	v_div_scale_f32 v10, s[4:5], v9, v9, 2.0
	v_rcp_f32_e32 v11, v10
	s_nop 0
	v_fma_f32 v16, -v10, v11, 1.0
	v_fmac_f32_e32 v11, v16, v11
	v_div_scale_f32 v16, vcc, 2.0, v9, 2.0
	v_mul_f32_e32 v17, v16, v11
	v_fma_f32 v22, -v10, v17, v16
	v_fmac_f32_e32 v17, v22, v11
	v_fma_f32 v10, -v10, v17, v16
	v_div_fmas_f32 v10, v10, v11, v17
	v_div_fixup_f32 v9, v10, v9, 2.0
	v_div_scale_f32 v10, s[4:5], v8, v8, 2.0
	v_rcp_f32_e32 v11, v10
	s_nop 0
	v_fma_f32 v16, -v10, v11, 1.0
	v_fmac_f32_e32 v11, v16, v11
	v_div_scale_f32 v16, vcc, 2.0, v8, 2.0
	v_mul_f32_e32 v17, v16, v11
	v_fma_f32 v22, -v10, v17, v16
	v_fmac_f32_e32 v17, v22, v11
	v_fma_f32 v10, -v10, v17, v16
	v_div_fmas_f32 v10, v10, v11, v17
	v_div_fixup_f32 v8, v10, v8, 2.0
	v_pk_add_f32 v[16:17], v[8:9], 1.0 op_sel_hi:[1,0] neg_lo:[1,0] neg_hi:[1,0]
	v_cvt_pk_bf16_f32 v8, v18, v19
	v_cvt_pk_bf16_f32 v9, v20, v21
	v_cvt_pk_bf16_f32 v10, v14, v15
	v_cvt_pk_bf16_f32 v11, v16, v17
	global_load_dwordx4 v[14:17], v[28:29], off offset:64
	s_waitcnt vmcnt(0)
	v_lshlrev_b32_e32 v20, 16, v14
	v_and_b32_e32 v21, 0xffff0000, v14
	v_lshlrev_b32_e32 v22, 16, v15
	v_and_b32_e32 v23, 0xffff0000, v15
	global_load_dwordx4 v[12:15], v[12:13], off offset:64
	v_lshlrev_b32_e32 v26, 16, v16
	v_and_b32_e32 v27, 0xffff0000, v16
	v_lshlrev_b32_e32 v30, 16, v17
	v_and_b32_e32 v31, 0xffff0000, v17
	s_waitcnt vmcnt(0)
	v_cndmask_b32_e64 v15, v15, 0, s[38:39]
	v_cndmask_b32_e64 v14, v14, 0, s[38:39]
	v_cndmask_b32_e64 v13, v13, 0, s[38:39]
	v_cndmask_b32_e64 v12, v12, 0, s[38:39]
	v_lshlrev_b32_e32 v42, 16, v12
	v_and_b32_e32 v43, 0xffff0000, v12
	v_lshlrev_b32_e32 v44, 16, v13
	v_and_b32_e32 v45, 0xffff0000, v13
	v_lshlrev_b32_e32 v46, 16, v14
	v_and_b32_e32 v47, 0xffff0000, v14
	v_lshlrev_b32_e32 v48, 16, v15
	v_and_b32_e32 v49, 0xffff0000, v15
	global_load_dwordx4 v[12:15], v[174:175], off offset:144
	global_load_dwordx4 v[16:19], v[174:175], off offset:128
	v_sub_f32_e32 v43, v43, v21
	v_sub_f32_e32 v42, v42, v20
	v_sub_f32_e32 v45, v45, v23
	v_sub_f32_e32 v44, v44, v22
	s_waitcnt vmcnt(0)
	v_pk_fma_f32 v[18:19], v[18:19], v[44:45], v[22:23]
	v_pk_fma_f32 v[16:17], v[16:17], v[42:43], v[20:21]
	v_sub_f32_e32 v21, v47, v27
	v_sub_f32_e32 v20, v46, v26
	v_sub_f32_e32 v23, v49, v31
	v_sub_f32_e32 v22, v48, v30
	v_pk_fma_f32 v[22:23], v[14:15], v[22:23], v[30:31]
	v_pk_fma_f32 v[14:15], v[12:13], v[20:21], v[26:27]
	v_cvt_pk_bf16_f32 v12, v16, v17
	v_cvt_pk_bf16_f32 v13, v18, v19
	v_cvt_pk_bf16_f32 v14, v14, v15
	v_cvt_pk_bf16_f32 v15, v22, v23
	global_load_dwordx4 v[16:19], v[24:25], off offset:128
	v_lshl_add_u64 v[26:27], v[32:33], 0, s[8:9]
	v_lshl_add_u64 v[30:31], v[32:33], 0, s[12:13]
	v_lshl_add_u64 v[32:33], v[32:33], 0, v[166:167]
	s_waitcnt vmcnt(0)
	v_lshlrev_b32_e32 v46, 16, v16
	v_and_b32_e32 v47, 0xffff0000, v16
	v_lshlrev_b32_e32 v48, 16, v17
	v_and_b32_e32 v49, 0xffff0000, v17
	v_lshl_add_u64 v[16:17], v[26:27], 0, v[186:187]
	v_lshlrev_b32_e32 v20, 16, v18
	v_and_b32_e32 v21, 0xffff0000, v18
	v_lshlrev_b32_e32 v22, 16, v19
	v_and_b32_e32 v23, 0xffff0000, v19
	global_load_dwordx4 v[16:19], v[16:17], off
	s_waitcnt vmcnt(0)
	v_cndmask_b32_e64 v19, v19, 0, s[36:37]
	v_cndmask_b32_e64 v18, v18, 0, s[36:37]
	v_cndmask_b32_e64 v17, v17, 0, s[36:37]
	v_cndmask_b32_e64 v16, v16, 0, s[36:37]
	v_lshlrev_b32_e32 v50, 16, v16
	v_and_b32_e32 v51, 0xffff0000, v16
	v_lshlrev_b32_e32 v52, 16, v17
	v_and_b32_e32 v53, 0xffff0000, v17
	v_lshlrev_b32_e32 v54, 16, v18
	v_and_b32_e32 v55, 0xffff0000, v18
	v_lshlrev_b32_e32 v58, 16, v19
	v_and_b32_e32 v59, 0xffff0000, v19
	global_load_dwordx4 v[16:19], v[172:173], off offset:272
	global_load_dwordx4 v[42:45], v[172:173], off offset:256
	v_sub_f32_e32 v51, v51, v47
	v_sub_f32_e32 v50, v50, v46
	v_sub_f32_e32 v53, v53, v49
	v_sub_f32_e32 v52, v52, v48
	s_waitcnt vmcnt(0)
	v_pk_fma_f32 v[42:43], v[42:43], v[50:51], v[46:47]
	s_nop 0
	v_add_f32_e32 v42, v42, v42
	v_add_f32_e32 v43, v43, v43
	v_mul_f32_e32 v42, 0x3fb8aa3b, v42
	v_mul_f32_e32 v43, 0x3fb8aa3b, v43
	v_exp_f32_e32 v42, v42
	v_exp_f32_e32 v43, v43
	v_pk_fma_f32 v[44:45], v[44:45], v[52:53], v[48:49]
	v_pk_add_f32 v[42:43], v[42:43], 1.0 op_sel_hi:[1,0]
	s_nop 0
	v_div_scale_f32 v46, s[4:5], v43, v43, 2.0
	v_rcp_f32_e32 v47, v46
	v_add_f32_e32 v44, v44, v44
	v_add_f32_e32 v45, v45, v45
	v_mul_f32_e32 v44, 0x3fb8aa3b, v44
	v_fma_f32 v48, -v46, v47, 1.0
	v_fmac_f32_e32 v47, v48, v47
	v_div_scale_f32 v48, vcc, 2.0, v43, 2.0
	v_mul_f32_e32 v49, v48, v47
	v_fma_f32 v50, -v46, v49, v48
	v_fmac_f32_e32 v49, v50, v47
	v_fma_f32 v46, -v46, v49, v48
	v_div_fmas_f32 v46, v46, v47, v49
	v_div_fixup_f32 v43, v46, v43, 2.0
	v_div_scale_f32 v46, s[4:5], v42, v42, 2.0
	v_rcp_f32_e32 v47, v46
	v_mul_f32_e32 v45, 0x3fb8aa3b, v45
	v_exp_f32_e32 v44, v44
	v_exp_f32_e32 v45, v45
	v_fma_f32 v48, -v46, v47, 1.0
	v_fmac_f32_e32 v47, v48, v47
	v_div_scale_f32 v48, vcc, 2.0, v42, 2.0
	v_mul_f32_e32 v49, v48, v47
	v_fma_f32 v50, -v46, v49, v48
	v_fmac_f32_e32 v49, v50, v47
	v_fma_f32 v46, -v46, v49, v48
	v_div_fmas_f32 v46, v46, v47, v49
	v_pk_add_f32 v[44:45], v[44:45], 1.0 op_sel_hi:[1,0]
	v_div_fixup_f32 v42, v46, v42, 2.0
	v_div_scale_f32 v46, s[4:5], v45, v45, 2.0
	v_rcp_f32_e32 v47, v46
	v_pk_add_f32 v[42:43], v[42:43], 1.0 op_sel_hi:[1,0] neg_lo:[1,0] neg_hi:[1,0]
	v_fma_f32 v48, -v46, v47, 1.0
	v_fmac_f32_e32 v47, v48, v47
	v_div_scale_f32 v48, vcc, 2.0, v45, 2.0
	v_mul_f32_e32 v49, v48, v47
	v_fma_f32 v50, -v46, v49, v48
	v_fmac_f32_e32 v49, v50, v47
	v_fma_f32 v46, -v46, v49, v48
	v_div_fmas_f32 v46, v46, v47, v49
	v_div_fixup_f32 v45, v46, v45, 2.0
	v_div_scale_f32 v46, s[4:5], v44, v44, 2.0
	v_rcp_f32_e32 v47, v46
	s_nop 0
	v_fma_f32 v48, -v46, v47, 1.0
	v_fmac_f32_e32 v47, v48, v47
	v_div_scale_f32 v48, vcc, 2.0, v44, 2.0
	v_mul_f32_e32 v49, v48, v47
	v_fma_f32 v50, -v46, v49, v48
	v_fmac_f32_e32 v49, v50, v47
	v_fma_f32 v46, -v46, v49, v48
	v_div_fmas_f32 v46, v46, v47, v49
	v_div_fixup_f32 v44, v46, v44, 2.0
	v_sub_f32_e32 v47, v55, v21
	v_sub_f32_e32 v46, v54, v20
	v_pk_fma_f32 v[16:17], v[16:17], v[46:47], v[20:21]
	v_sub_f32_e32 v49, v59, v23
	v_add_f32_e32 v16, v16, v16
	v_add_f32_e32 v17, v17, v17
	v_mul_f32_e32 v16, 0x3fb8aa3b, v16
	v_mul_f32_e32 v17, 0x3fb8aa3b, v17
	v_exp_f32_e32 v16, v16
	v_exp_f32_e32 v17, v17
	v_sub_f32_e32 v48, v58, v22
	v_pk_fma_f32 v[18:19], v[18:19], v[48:49], v[22:23]
	v_pk_add_f32 v[44:45], v[44:45], 1.0 op_sel_hi:[1,0] neg_lo:[1,0] neg_hi:[1,0]
	v_pk_add_f32 v[16:17], v[16:17], 1.0 op_sel_hi:[1,0]
	s_nop 0
	v_div_scale_f32 v20, s[4:5], v17, v17, 2.0
	v_rcp_f32_e32 v21, v20
	s_nop 0
	v_fma_f32 v22, -v20, v21, 1.0
	v_fmac_f32_e32 v21, v22, v21
	v_div_scale_f32 v22, vcc, 2.0, v17, 2.0
	v_mul_f32_e32 v23, v22, v21
	v_fma_f32 v46, -v20, v23, v22
	v_fmac_f32_e32 v23, v46, v21
	v_fma_f32 v20, -v20, v23, v22
	v_div_fmas_f32 v20, v20, v21, v23
	v_div_fixup_f32 v17, v20, v17, 2.0
	v_div_scale_f32 v20, s[4:5], v16, v16, 2.0
	v_rcp_f32_e32 v21, v20
	s_nop 0
	v_fma_f32 v22, -v20, v21, 1.0
	v_fmac_f32_e32 v21, v22, v21
	v_div_scale_f32 v22, vcc, 2.0, v16, 2.0
	v_mul_f32_e32 v23, v22, v21
	v_fma_f32 v46, -v20, v23, v22
	v_fmac_f32_e32 v23, v46, v21
	v_fma_f32 v20, -v20, v23, v22
	v_div_fmas_f32 v20, v20, v21, v23
	v_div_fixup_f32 v16, v20, v16, 2.0
	v_pk_add_f32 v[20:21], v[16:17], 1.0 op_sel_hi:[1,0] neg_lo:[1,0] neg_hi:[1,0]
	v_add_f32_e32 v16, v18, v18
	v_add_f32_e32 v17, v19, v19
	v_mul_f32_e32 v16, 0x3fb8aa3b, v16
	v_mul_f32_e32 v17, 0x3fb8aa3b, v17
	v_exp_f32_e32 v16, v16
	v_exp_f32_e32 v17, v17
	s_nop 0
	v_pk_add_f32 v[16:17], v[16:17], 1.0 op_sel_hi:[1,0]
	s_nop 0
	v_div_scale_f32 v18, s[4:5], v17, v17, 2.0
	v_rcp_f32_e32 v19, v18
	s_nop 0
	v_fma_f32 v22, -v18, v19, 1.0
	v_fmac_f32_e32 v19, v22, v19
	v_div_scale_f32 v22, vcc, 2.0, v17, 2.0
	v_mul_f32_e32 v23, v22, v19
	v_fma_f32 v46, -v18, v23, v22
	v_fmac_f32_e32 v23, v46, v19
	v_fma_f32 v18, -v18, v23, v22
	v_div_fmas_f32 v18, v18, v19, v23
	v_div_fixup_f32 v17, v18, v17, 2.0
	v_div_scale_f32 v18, s[4:5], v16, v16, 2.0
	v_rcp_f32_e32 v19, v18
	s_nop 0
	v_fma_f32 v22, -v18, v19, 1.0
	v_fmac_f32_e32 v19, v22, v19
	v_div_scale_f32 v22, vcc, 2.0, v16, 2.0
	v_mul_f32_e32 v23, v22, v19
	v_fma_f32 v46, -v18, v23, v22
	v_fmac_f32_e32 v23, v46, v19
	v_fma_f32 v18, -v18, v23, v22
	v_div_fmas_f32 v18, v18, v19, v23
	v_div_fixup_f32 v16, v18, v16, 2.0
	v_pk_add_f32 v[22:23], v[16:17], 1.0 op_sel_hi:[1,0] neg_lo:[1,0] neg_hi:[1,0]
	v_cvt_pk_bf16_f32 v16, v42, v43
	v_cvt_pk_bf16_f32 v17, v44, v45
	v_cvt_pk_bf16_f32 v18, v20, v21
	v_cvt_pk_bf16_f32 v19, v22, v23
	global_load_dwordx4 v[20:23], v[28:29], off offset:128
	s_waitcnt vmcnt(0)
	v_lshlrev_b32_e32 v46, 16, v20
	v_and_b32_e32 v47, 0xffff0000, v20
	v_lshlrev_b32_e32 v48, 16, v21
	v_and_b32_e32 v49, 0xffff0000, v21
	v_lshl_add_u64 v[20:21], v[30:31], 0, v[186:187]
	v_lshlrev_b32_e32 v50, 16, v22
	v_and_b32_e32 v51, 0xffff0000, v22
	v_lshlrev_b32_e32 v52, 16, v23
	v_and_b32_e32 v53, 0xffff0000, v23
	global_load_dwordx4 v[20:23], v[20:21], off
	s_waitcnt vmcnt(0)
	v_cndmask_b32_e64 v23, v23, 0, s[36:37]
	v_cndmask_b32_e64 v22, v22, 0, s[36:37]
	v_cndmask_b32_e64 v21, v21, 0, s[36:37]
	v_cndmask_b32_e64 v20, v20, 0, s[36:37]
	v_lshlrev_b32_e32 v54, 16, v20
	v_and_b32_e32 v55, 0xffff0000, v20
	v_lshlrev_b32_e32 v58, 16, v21
	v_and_b32_e32 v59, 0xffff0000, v21
	v_lshlrev_b32_e32 v60, 16, v22
	v_and_b32_e32 v61, 0xffff0000, v22
	v_lshlrev_b32_e32 v62, 16, v23
	v_and_b32_e32 v63, 0xffff0000, v23
	global_load_dwordx4 v[20:23], v[174:175], off offset:272
	global_load_dwordx4 v[42:45], v[174:175], off offset:256
	v_sub_f32_e32 v55, v55, v47
	v_sub_f32_e32 v54, v54, v46
	v_sub_f32_e32 v59, v59, v49
	v_sub_f32_e32 v58, v58, v48
	s_waitcnt vmcnt(0)
	v_pk_fma_f32 v[44:45], v[44:45], v[58:59], v[48:49]
	v_pk_fma_f32 v[42:43], v[42:43], v[54:55], v[46:47]
	v_sub_f32_e32 v47, v61, v51
	v_sub_f32_e32 v46, v60, v50
	v_sub_f32_e32 v49, v63, v53
	v_sub_f32_e32 v48, v62, v52
	v_pk_fma_f32 v[48:49], v[22:23], v[48:49], v[52:53]
	v_pk_fma_f32 v[22:23], v[20:21], v[46:47], v[50:51]
	v_cvt_pk_bf16_f32 v20, v42, v43
	v_cvt_pk_bf16_f32 v21, v44, v45
	v_cvt_pk_bf16_f32 v22, v22, v23
	v_cvt_pk_bf16_f32 v23, v48, v49
	global_load_dwordx4 v[42:45], v[24:25], off offset:192
	v_lshl_add_u64 v[24:25], v[26:27], 0, v[188:189]
	global_load_dwordx4 v[24:27], v[24:25], off
	s_waitcnt vmcnt(1)
	v_lshlrev_b32_e32 v50, 16, v42
	v_and_b32_e32 v51, 0xffff0000, v42
	s_waitcnt vmcnt(0)
	v_cndmask_b32_e64 v27, v27, 0, s[36:37]
	v_cndmask_b32_e64 v26, v26, 0, s[36:37]
	v_cndmask_b32_e64 v25, v25, 0, s[36:37]
	v_cndmask_b32_e64 v24, v24, 0, s[36:37]
	v_lshlrev_b32_e32 v54, 16, v24
	v_and_b32_e32 v55, 0xffff0000, v24
	v_lshlrev_b32_e32 v58, 16, v25
	v_and_b32_e32 v59, 0xffff0000, v25
	v_lshlrev_b32_e32 v60, 16, v26
	v_and_b32_e32 v61, 0xffff0000, v26
	v_lshlrev_b32_e32 v62, 16, v27
	v_and_b32_e32 v63, 0xffff0000, v27
	global_load_dwordx4 v[24:27], v[172:173], off offset:400
	global_load_dwordx4 v[46:49], v[172:173], off offset:384
	v_sub_f32_e32 v55, v55, v51
	v_sub_f32_e32 v54, v54, v50
	v_lshlrev_b32_e32 v52, 16, v43
	v_and_b32_e32 v53, 0xffff0000, v43
	v_sub_f32_e32 v59, v59, v53
	v_sub_f32_e32 v58, v58, v52
	v_lshlrev_b32_e32 v42, 16, v44
	v_and_b32_e32 v43, 0xffff0000, v44
	v_lshlrev_b32_e32 v44, 16, v45
	v_and_b32_e32 v45, 0xffff0000, v45
	s_waitcnt vmcnt(0)
	v_pk_fma_f32 v[46:47], v[46:47], v[54:55], v[50:51]
	s_nop 0
	v_add_f32_e32 v46, v46, v46
	v_add_f32_e32 v47, v47, v47
	v_mul_f32_e32 v46, 0x3fb8aa3b, v46
	v_mul_f32_e32 v47, 0x3fb8aa3b, v47
	v_exp_f32_e32 v46, v46
	v_exp_f32_e32 v47, v47
	v_pk_fma_f32 v[48:49], v[48:49], v[58:59], v[52:53]
	v_pk_add_f32 v[46:47], v[46:47], 1.0 op_sel_hi:[1,0]
	s_nop 0
	v_div_scale_f32 v50, s[4:5], v47, v47, 2.0
	v_rcp_f32_e32 v51, v50
	v_add_f32_e32 v48, v48, v48
	v_add_f32_e32 v49, v49, v49
	v_mul_f32_e32 v48, 0x3fb8aa3b, v48
	v_fma_f32 v52, -v50, v51, 1.0
	v_fmac_f32_e32 v51, v52, v51
	v_div_scale_f32 v52, vcc, 2.0, v47, 2.0
	v_mul_f32_e32 v53, v52, v51
	v_fma_f32 v54, -v50, v53, v52
	v_fmac_f32_e32 v53, v54, v51
	v_fma_f32 v50, -v50, v53, v52
	v_div_fmas_f32 v50, v50, v51, v53
	v_div_fixup_f32 v47, v50, v47, 2.0
	v_div_scale_f32 v50, s[4:5], v46, v46, 2.0
	v_rcp_f32_e32 v51, v50
	v_mul_f32_e32 v49, 0x3fb8aa3b, v49
	v_exp_f32_e32 v48, v48
	v_exp_f32_e32 v49, v49
	v_fma_f32 v52, -v50, v51, 1.0
	v_fmac_f32_e32 v51, v52, v51
	v_div_scale_f32 v52, vcc, 2.0, v46, 2.0
	v_mul_f32_e32 v53, v52, v51
	v_fma_f32 v54, -v50, v53, v52
	v_fmac_f32_e32 v53, v54, v51
	v_fma_f32 v50, -v50, v53, v52
	v_div_fmas_f32 v50, v50, v51, v53
	v_pk_add_f32 v[48:49], v[48:49], 1.0 op_sel_hi:[1,0]
	v_div_fixup_f32 v46, v50, v46, 2.0
	v_div_scale_f32 v50, s[4:5], v49, v49, 2.0
	v_rcp_f32_e32 v51, v50
	v_pk_add_f32 v[46:47], v[46:47], 1.0 op_sel_hi:[1,0] neg_lo:[1,0] neg_hi:[1,0]
	v_fma_f32 v52, -v50, v51, 1.0
	v_fmac_f32_e32 v51, v52, v51
	v_div_scale_f32 v52, vcc, 2.0, v49, 2.0
	v_mul_f32_e32 v53, v52, v51
	v_fma_f32 v54, -v50, v53, v52
	v_fmac_f32_e32 v53, v54, v51
	v_fma_f32 v50, -v50, v53, v52
	v_div_fmas_f32 v50, v50, v51, v53
	v_div_fixup_f32 v49, v50, v49, 2.0
	v_div_scale_f32 v50, s[4:5], v48, v48, 2.0
	v_rcp_f32_e32 v51, v50
	s_nop 0
	v_fma_f32 v52, -v50, v51, 1.0
	v_fmac_f32_e32 v51, v52, v51
	v_div_scale_f32 v52, vcc, 2.0, v48, 2.0
	v_mul_f32_e32 v53, v52, v51
	v_fma_f32 v54, -v50, v53, v52
	v_fmac_f32_e32 v53, v54, v51
	v_fma_f32 v50, -v50, v53, v52
	v_div_fmas_f32 v50, v50, v51, v53
	v_div_fixup_f32 v48, v50, v48, 2.0
	v_sub_f32_e32 v51, v61, v43
	v_sub_f32_e32 v50, v60, v42
	v_pk_fma_f32 v[24:25], v[24:25], v[50:51], v[42:43]
	v_sub_f32_e32 v53, v63, v45
	v_add_f32_e32 v24, v24, v24
	v_add_f32_e32 v25, v25, v25
	v_mul_f32_e32 v24, 0x3fb8aa3b, v24
	v_mul_f32_e32 v25, 0x3fb8aa3b, v25
	v_exp_f32_e32 v24, v24
	v_exp_f32_e32 v25, v25
	v_sub_f32_e32 v52, v62, v44
	v_pk_fma_f32 v[26:27], v[26:27], v[52:53], v[44:45]
	v_pk_add_f32 v[48:49], v[48:49], 1.0 op_sel_hi:[1,0] neg_lo:[1,0] neg_hi:[1,0]
	v_pk_add_f32 v[24:25], v[24:25], 1.0 op_sel_hi:[1,0]
	s_nop 0
	v_div_scale_f32 v42, s[4:5], v25, v25, 2.0
	v_rcp_f32_e32 v43, v42
	s_nop 0
	v_fma_f32 v44, -v42, v43, 1.0
	v_fmac_f32_e32 v43, v44, v43
	v_div_scale_f32 v44, vcc, 2.0, v25, 2.0
	v_mul_f32_e32 v45, v44, v43
	v_fma_f32 v50, -v42, v45, v44
	v_fmac_f32_e32 v45, v50, v43
	v_fma_f32 v42, -v42, v45, v44
	v_div_fmas_f32 v42, v42, v43, v45
	v_div_fixup_f32 v25, v42, v25, 2.0
	v_div_scale_f32 v42, s[4:5], v24, v24, 2.0
	v_rcp_f32_e32 v43, v42
	s_nop 0
	v_fma_f32 v44, -v42, v43, 1.0
	v_fmac_f32_e32 v43, v44, v43
	v_div_scale_f32 v44, vcc, 2.0, v24, 2.0
	v_mul_f32_e32 v45, v44, v43
	v_fma_f32 v50, -v42, v45, v44
	v_fmac_f32_e32 v45, v50, v43
	v_fma_f32 v42, -v42, v45, v44
	v_div_fmas_f32 v42, v42, v43, v45
	v_div_fixup_f32 v24, v42, v24, 2.0
	v_pk_add_f32 v[42:43], v[24:25], 1.0 op_sel_hi:[1,0] neg_lo:[1,0] neg_hi:[1,0]
	v_add_f32_e32 v24, v26, v26
	v_add_f32_e32 v25, v27, v27
	v_mul_f32_e32 v24, 0x3fb8aa3b, v24
	v_mul_f32_e32 v25, 0x3fb8aa3b, v25
	v_exp_f32_e32 v24, v24
	v_exp_f32_e32 v25, v25
	s_nop 0
	v_pk_add_f32 v[24:25], v[24:25], 1.0 op_sel_hi:[1,0]
	s_nop 0
	v_div_scale_f32 v26, s[4:5], v25, v25, 2.0
	v_rcp_f32_e32 v27, v26
	s_nop 0
	v_fma_f32 v44, -v26, v27, 1.0
	v_fmac_f32_e32 v27, v44, v27
	v_div_scale_f32 v44, vcc, 2.0, v25, 2.0
	v_mul_f32_e32 v45, v44, v27
	v_fma_f32 v50, -v26, v45, v44
	v_fmac_f32_e32 v45, v50, v27
	v_fma_f32 v26, -v26, v45, v44
	v_div_fmas_f32 v26, v26, v27, v45
	v_div_fixup_f32 v25, v26, v25, 2.0
	v_div_scale_f32 v26, s[4:5], v24, v24, 2.0
	v_rcp_f32_e32 v27, v26
	s_mov_b64 s[4:5], 0x2c00
	v_fma_f32 v44, -v26, v27, 1.0
	v_fmac_f32_e32 v27, v44, v27
	v_div_scale_f32 v44, vcc, 2.0, v24, 2.0
	v_mul_f32_e32 v45, v44, v27
	v_fma_f32 v50, -v26, v45, v44
	v_fmac_f32_e32 v45, v50, v27
	v_fma_f32 v26, -v26, v45, v44
	v_div_fmas_f32 v26, v26, v27, v45
	v_div_fixup_f32 v24, v26, v24, 2.0
	v_pk_add_f32 v[44:45], v[24:25], 1.0 op_sel_hi:[1,0] neg_lo:[1,0] neg_hi:[1,0]
	v_cvt_pk_bf16_f32 v24, v46, v47
	v_cvt_pk_bf16_f32 v25, v48, v49
	v_cvt_pk_bf16_f32 v26, v42, v43
	v_cvt_pk_bf16_f32 v27, v44, v45
	global_load_dwordx4 v[42:45], v[28:29], off offset:192
	v_lshl_add_u64 v[28:29], v[30:31], 0, v[188:189]
	global_load_dwordx4 v[28:31], v[28:29], off
	s_waitcnt vmcnt(1)
	v_lshlrev_b32_e32 v46, 16, v42
	v_and_b32_e32 v47, 0xffff0000, v42
	s_waitcnt vmcnt(0)
	v_cndmask_b32_e64 v31, v31, 0, s[36:37]
	v_cndmask_b32_e64 v30, v30, 0, s[36:37]
	v_cndmask_b32_e64 v29, v29, 0, s[36:37]
	v_cndmask_b32_e64 v28, v28, 0, s[36:37]
	v_lshlrev_b32_e32 v48, 16, v43
	v_and_b32_e32 v49, 0xffff0000, v43
	v_lshlrev_b32_e32 v50, 16, v44
	v_and_b32_e32 v51, 0xffff0000, v44
	v_lshlrev_b32_e32 v52, 16, v45
	v_and_b32_e32 v53, 0xffff0000, v45
	v_lshlrev_b32_e32 v54, 16, v28
	v_and_b32_e32 v55, 0xffff0000, v28
	v_lshlrev_b32_e32 v58, 16, v29
	v_and_b32_e32 v59, 0xffff0000, v29
	v_lshlrev_b32_e32 v60, 16, v30
	v_and_b32_e32 v61, 0xffff0000, v30
	v_lshlrev_b32_e32 v62, 16, v31
	v_and_b32_e32 v63, 0xffff0000, v31
	global_load_dwordx4 v[28:31], v[174:175], off offset:400
	global_load_dwordx4 v[42:45], v[174:175], off offset:384
	v_sub_f32_e32 v55, v55, v47
	v_sub_f32_e32 v54, v54, v46
	v_sub_f32_e32 v59, v59, v49
	v_sub_f32_e32 v58, v58, v48
	s_waitcnt vmcnt(0)
	v_pk_fma_f32 v[44:45], v[44:45], v[58:59], v[48:49]
	v_pk_fma_f32 v[42:43], v[42:43], v[54:55], v[46:47]
	v_sub_f32_e32 v47, v61, v51
	v_sub_f32_e32 v46, v60, v50
	v_sub_f32_e32 v49, v63, v53
	v_sub_f32_e32 v48, v62, v52
	v_pk_fma_f32 v[48:49], v[30:31], v[48:49], v[52:53]
	v_pk_fma_f32 v[30:31], v[28:29], v[46:47], v[50:51]
	v_cvt_pk_bf16_f32 v28, v42, v43
	v_cvt_pk_bf16_f32 v29, v44, v45
	v_cvt_pk_bf16_f32 v30, v30, v31
	v_cvt_pk_bf16_f32 v31, v48, v49
	v_lshl_add_u64 v[54:55], v[34:35], 0, s[4:5]
	global_load_dwordx4 v[34:37], v[36:37], off offset:3072
	v_lshl_add_u64 v[58:59], v[32:33], 0, s[4:5]
	v_add_co_u32_e32 v32, vcc, s79, v32
	v_lshl_add_u64 v[52:53], v[40:41], 0, s[4:5]
	s_nop 0
	v_addc_co_u32_e32 v33, vcc, 0, v33, vcc
	s_waitcnt vmcnt(0)
	v_lshlrev_b32_e32 v48, 16, v34
	v_and_b32_e32 v49, 0xffff0000, v34
	v_lshlrev_b32_e32 v46, 16, v35
	v_and_b32_e32 v47, 0xffff0000, v35
	v_lshlrev_b32_e32 v44, 16, v36
	v_and_b32_e32 v45, 0xffff0000, v36
	v_lshlrev_b32_e32 v42, 16, v37
	v_and_b32_e32 v43, 0xffff0000, v37
	global_load_dwordx4 v[34:37], v[38:39], off offset:3072
	s_waitcnt vmcnt(0)
	v_cndmask_b32_e64 v35, v35, 0, s[38:39]
	v_cndmask_b32_e64 v34, v34, 0, s[38:39]
	v_lshlrev_b32_e32 v70, 16, v34
	v_and_b32_e32 v71, 0xffff0000, v34
	v_lshlrev_b32_e32 v68, 16, v35
	v_and_b32_e32 v69, 0xffff0000, v35
	global_load_dwordx4 v[32:35], v[32:33], off offset:3072
	v_cndmask_b32_e64 v37, v37, 0, s[38:39]
	v_cndmask_b32_e64 v36, v36, 0, s[38:39]
	v_lshlrev_b32_e32 v40, 16, v36
	v_and_b32_e32 v41, 0xffff0000, v36
	v_lshlrev_b32_e32 v50, 16, v37
	v_and_b32_e32 v51, 0xffff0000, v37
	v_sub_f32_e32 v71, v71, v49
	v_sub_f32_e32 v70, v70, v48
	v_sub_f32_e32 v69, v69, v47
	v_sub_f32_e32 v68, v68, v46
	v_sub_f32_e32 v41, v41, v45
	v_sub_f32_e32 v40, v40, v44
	s_waitcnt vmcnt(0)
	v_cndmask_b32_e64 v35, v35, 0, s[36:37]
	v_cndmask_b32_e64 v34, v34, 0, s[36:37]
	v_cndmask_b32_e64 v33, v33, 0, s[36:37]
	v_cndmask_b32_e64 v32, v32, 0, s[36:37]
	v_lshlrev_b32_e32 v72, 16, v32
	v_and_b32_e32 v73, 0xffff0000, v32
	v_lshlrev_b32_e32 v74, 16, v33
	v_and_b32_e32 v75, 0xffff0000, v33
	v_lshlrev_b32_e32 v76, 16, v34
	v_and_b32_e32 v77, 0xffff0000, v34
	v_lshlrev_b32_e32 v78, 16, v35
	v_and_b32_e32 v79, 0xffff0000, v35
	global_load_dwordx4 v[32:35], v[176:177], off offset:16
	global_load_dwordx4 v[60:63], v[176:177], off
	global_load_dwordx4 v[36:39], v[176:177], off offset:656
	global_load_dwordx4 v[64:67], v[176:177], off offset:640
	s_waitcnt vmcnt(3)
	v_pk_fma_f32 v[32:33], v[32:33], v[40:41], v[44:45]
	s_waitcnt vmcnt(2)
	v_pk_fma_f32 v[60:61], v[60:61], v[70:71], v[48:49]
	v_sub_f32_e32 v49, v73, v49
	v_sub_f32_e32 v48, v72, v48
	s_waitcnt vmcnt(0)
	v_pk_fma_f32 v[48:49], v[64:65], v[48:49], v[60:61]
	v_pk_fma_f32 v[62:63], v[62:63], v[68:69], v[46:47]
	v_mul_f32_e32 v48, 0xbfb8aa3b, v48
	v_mul_f32_e32 v49, 0xbfb8aa3b, v49
	v_exp_f32_e32 v48, v48
	v_exp_f32_e32 v49, v49
	v_sub_f32_e32 v47, v75, v47
	v_sub_f32_e32 v46, v74, v46
	v_pk_fma_f32 v[46:47], v[66:67], v[46:47], v[62:63]
	v_pk_add_f32 v[48:49], v[48:49], 1.0 op_sel_hi:[1,0]
	v_mul_f32_e32 v46, 0xbfb8aa3b, v46
	v_div_scale_f32 v60, s[4:5], v49, v49, 1.0
	v_rcp_f32_e32 v61, v60
	v_mul_f32_e32 v47, 0xbfb8aa3b, v47
	v_exp_f32_e32 v46, v46
	v_exp_f32_e32 v47, v47
	v_fma_f32 v62, -v60, v61, 1.0
	v_fmac_f32_e32 v61, v62, v61
	v_div_scale_f32 v62, vcc, 1.0, v49, 1.0
	v_mul_f32_e32 v63, v62, v61
	v_fma_f32 v64, -v60, v63, v62
	v_fmac_f32_e32 v63, v64, v61
	v_fma_f32 v60, -v60, v63, v62
	v_div_fmas_f32 v60, v60, v61, v63
	v_div_fixup_f32 v49, v60, v49, 1.0
	v_div_scale_f32 v60, s[4:5], v48, v48, 1.0
	v_rcp_f32_e32 v61, v60
	v_pk_add_f32 v[46:47], v[46:47], 1.0 op_sel_hi:[1,0]
	v_sub_f32_e32 v41, v77, v45
	v_sub_f32_e32 v40, v76, v44
	v_fma_f32 v62, -v60, v61, 1.0
	v_fmac_f32_e32 v61, v62, v61
	v_div_scale_f32 v62, vcc, 1.0, v48, 1.0
	v_mul_f32_e32 v63, v62, v61
	v_fma_f32 v64, -v60, v63, v62
	v_fmac_f32_e32 v63, v64, v61
	v_fma_f32 v60, -v60, v63, v62
	v_div_fmas_f32 v60, v60, v61, v63
	v_div_fixup_f32 v48, v60, v48, 1.0
	v_div_scale_f32 v60, s[4:5], v47, v47, 1.0
	v_rcp_f32_e32 v61, v60
	v_pk_fma_f32 v[32:33], v[36:37], v[40:41], v[32:33]
	v_fma_f32 v62, -v60, v61, 1.0
	v_fmac_f32_e32 v61, v62, v61
	v_div_scale_f32 v62, vcc, 1.0, v47, 1.0
	v_mul_f32_e32 v63, v62, v61
	v_fma_f32 v64, -v60, v63, v62
	v_fmac_f32_e32 v63, v64, v61
	v_fma_f32 v60, -v60, v63, v62
	v_div_fmas_f32 v60, v60, v61, v63
	v_div_fixup_f32 v60, v60, v47, 1.0
	v_div_scale_f32 v47, s[4:5], v46, v46, 1.0
	v_rcp_f32_e32 v61, v47
	v_mul_f32_e32 v32, 0xbfb8aa3b, v32
	v_mul_f32_e32 v33, 0xbfb8aa3b, v33
	v_exp_f32_e32 v32, v32
	v_exp_f32_e32 v33, v33
	v_fma_f32 v62, -v47, v61, 1.0
	v_fmac_f32_e32 v61, v62, v61
	v_div_scale_f32 v62, vcc, 1.0, v46, 1.0
	v_mul_f32_e32 v63, v62, v61
	v_fma_f32 v64, -v47, v63, v62
	v_pk_add_f32 v[32:33], v[32:33], 1.0 op_sel_hi:[1,0]
	v_fmac_f32_e32 v63, v64, v61
	v_div_scale_f32 v36, s[4:5], v33, v33, 1.0
	v_fma_f32 v47, -v47, v63, v62
	v_rcp_f32_e32 v37, v36
	v_div_fmas_f32 v47, v47, v61, v63
	v_div_fixup_f32 v61, v47, v46, 1.0
	v_sub_f32_e32 v47, v51, v43
	v_sub_f32_e32 v46, v50, v42
	v_pk_fma_f32 v[34:35], v[34:35], v[46:47], v[42:43]
	v_sub_f32_e32 v43, v79, v43
	v_sub_f32_e32 v42, v78, v42
	v_pk_fma_f32 v[34:35], v[38:39], v[42:43], v[34:35]
	v_fma_f32 v38, -v36, v37, 1.0
	v_fmac_f32_e32 v37, v38, v37
	v_div_scale_f32 v38, vcc, 1.0, v33, 1.0
	v_mul_f32_e32 v39, v38, v37
	v_fma_f32 v40, -v36, v39, v38
	v_fmac_f32_e32 v39, v40, v37
	v_fma_f32 v36, -v36, v39, v38
	v_div_fmas_f32 v36, v36, v37, v39
	v_div_fixup_f32 v36, v36, v33, 1.0
	v_div_scale_f32 v33, s[4:5], v32, v32, 1.0
	v_rcp_f32_e32 v37, v33
	s_nop 0
	v_fma_f32 v38, -v33, v37, 1.0
	v_fmac_f32_e32 v37, v38, v37
	v_div_scale_f32 v38, vcc, 1.0, v32, 1.0
	v_mul_f32_e32 v39, v38, v37
	v_fma_f32 v40, -v33, v39, v38
	v_fmac_f32_e32 v39, v40, v37
	v_fma_f32 v33, -v33, v39, v38
	v_div_fmas_f32 v33, v33, v37, v39
	v_div_fixup_f32 v37, v33, v32, 1.0
	v_mul_f32_e32 v32, 0xbfb8aa3b, v34
	v_mul_f32_e32 v33, 0xbfb8aa3b, v35
	v_exp_f32_e32 v32, v32
	v_exp_f32_e32 v33, v33
	s_nop 0
	v_pk_add_f32 v[32:33], v[32:33], 1.0 op_sel_hi:[1,0]
	s_nop 0
	v_div_scale_f32 v34, s[4:5], v33, v33, 1.0
	v_rcp_f32_e32 v35, v34
	s_nop 0
	v_fma_f32 v38, -v34, v35, 1.0
	v_fmac_f32_e32 v35, v38, v35
	v_div_scale_f32 v38, vcc, 1.0, v33, 1.0
	v_mul_f32_e32 v39, v38, v35
	v_fma_f32 v40, -v34, v39, v38
	v_fmac_f32_e32 v39, v40, v35
	v_fma_f32 v34, -v34, v39, v38
	v_div_fmas_f32 v34, v34, v35, v39
	v_div_fixup_f32 v35, v34, v33, 1.0
	v_div_scale_f32 v33, s[4:5], v32, v32, 1.0
	v_rcp_f32_e32 v34, v33
	s_nop 0
	v_fma_f32 v38, -v33, v34, 1.0
	v_fmac_f32_e32 v34, v38, v34
	v_div_scale_f32 v38, vcc, 1.0, v32, 1.0
	v_mul_f32_e32 v39, v38, v34
	v_fma_f32 v40, -v33, v39, v38
	v_fmac_f32_e32 v39, v40, v34
	v_fma_f32 v33, -v33, v39, v38
	v_div_fmas_f32 v33, v33, v34, v39
	v_div_fixup_f32 v38, v33, v32, 1.0
	v_cvt_pk_bf16_f32 v32, v48, v49
	v_cvt_pk_bf16_f32 v33, v61, v60
	v_cvt_pk_bf16_f32 v34, v37, v36
	v_cvt_pk_bf16_f32 v35, v38, v35
	global_load_dwordx4 v[36:39], v[54:55], off offset:64
	s_waitcnt vmcnt(0)
	v_lshlrev_b32_e32 v50, 16, v36
	v_and_b32_e32 v51, 0xffff0000, v36
	v_lshlrev_b32_e32 v48, 16, v37
	v_and_b32_e32 v49, 0xffff0000, v37
	v_lshlrev_b32_e32 v46, 16, v38
	v_and_b32_e32 v47, 0xffff0000, v38
	v_lshlrev_b32_e32 v44, 16, v39
	v_and_b32_e32 v45, 0xffff0000, v39
	global_load_dwordx4 v[36:39], v[52:53], off offset:64
	s_waitcnt vmcnt(0)
	v_cndmask_b32_e64 v39, v39, 0, s[38:39]
	v_cndmask_b32_e64 v38, v38, 0, s[38:39]
	v_cndmask_b32_e64 v37, v37, 0, s[38:39]
	v_cndmask_b32_e64 v36, v36, 0, s[38:39]
	v_lshlrev_b32_e32 v72, 16, v36
	v_and_b32_e32 v73, 0xffff0000, v36
	v_lshlrev_b32_e32 v70, 16, v37
	v_and_b32_e32 v71, 0xffff0000, v37
	v_lshlrev_b32_e32 v60, 16, v38
	v_and_b32_e32 v61, 0xffff0000, v38
	v_lshlrev_b32_e32 v74, 16, v39
	v_and_b32_e32 v75, 0xffff0000, v39
	global_load_dwordx4 v[36:39], v[58:59], off offset:64
	v_sub_f32_e32 v73, v73, v51
	v_sub_f32_e32 v72, v72, v50
	v_sub_f32_e32 v71, v71, v49
	v_sub_f32_e32 v70, v70, v48
	s_waitcnt vmcnt(0)
	v_cndmask_b32_e64 v39, v39, 0, s[36:37]
	v_cndmask_b32_e64 v38, v38, 0, s[36:37]
	v_cndmask_b32_e64 v37, v37, 0, s[36:37]
	v_cndmask_b32_e64 v36, v36, 0, s[36:37]
	v_lshlrev_b32_e32 v76, 16, v36
	v_and_b32_e32 v77, 0xffff0000, v36
	v_lshlrev_b32_e32 v78, 16, v37
	v_and_b32_e32 v79, 0xffff0000, v37
	v_lshlrev_b32_e32 v80, 16, v38
	v_and_b32_e32 v81, 0xffff0000, v38
	v_lshlrev_b32_e32 v82, 16, v39
	v_and_b32_e32 v83, 0xffff0000, v39
	global_load_dwordx4 v[36:39], v[176:177], off offset:144
	global_load_dwordx4 v[62:65], v[176:177], off offset:128
	global_load_dwordx4 v[40:43], v[176:177], off offset:784
	global_load_dwordx4 v[66:69], v[176:177], off offset:768
	s_waitcnt vmcnt(2)
	v_pk_fma_f32 v[62:63], v[62:63], v[72:73], v[50:51]
	v_sub_f32_e32 v51, v77, v51
	v_sub_f32_e32 v50, v76, v50
	s_waitcnt vmcnt(0)
	v_pk_fma_f32 v[50:51], v[66:67], v[50:51], v[62:63]
	v_pk_fma_f32 v[64:65], v[64:65], v[70:71], v[48:49]
	v_mul_f32_e32 v50, 0xbfb8aa3b, v50
	v_mul_f32_e32 v51, 0xbfb8aa3b, v51
	v_exp_f32_e32 v50, v50
	v_exp_f32_e32 v51, v51
	v_sub_f32_e32 v49, v79, v49
	v_sub_f32_e32 v48, v78, v48
	v_pk_fma_f32 v[48:49], v[68:69], v[48:49], v[64:65]
	v_pk_add_f32 v[50:51], v[50:51], 1.0 op_sel_hi:[1,0]
	v_mul_f32_e32 v48, 0xbfb8aa3b, v48
	v_div_scale_f32 v62, s[4:5], v51, v51, 1.0
	v_rcp_f32_e32 v63, v62
	v_mul_f32_e32 v49, 0xbfb8aa3b, v49
	v_exp_f32_e32 v48, v48
	v_exp_f32_e32 v49, v49
	v_fma_f32 v64, -v62, v63, 1.0
	v_fmac_f32_e32 v63, v64, v63
	v_div_scale_f32 v64, vcc, 1.0, v51, 1.0
	v_mul_f32_e32 v65, v64, v63
	v_fma_f32 v66, -v62, v65, v64
	v_fmac_f32_e32 v65, v66, v63
	v_fma_f32 v62, -v62, v65, v64
	v_div_fmas_f32 v62, v62, v63, v65
	v_div_fixup_f32 v62, v62, v51, 1.0
	v_div_scale_f32 v51, s[4:5], v50, v50, 1.0
	v_rcp_f32_e32 v63, v51
	v_pk_add_f32 v[48:49], v[48:49], 1.0 op_sel_hi:[1,0]
	v_fma_f32 v64, -v51, v63, 1.0
	v_fmac_f32_e32 v63, v64, v63
	v_div_scale_f32 v64, vcc, 1.0, v50, 1.0
	v_mul_f32_e32 v65, v64, v63
	v_fma_f32 v66, -v51, v65, v64
	v_fmac_f32_e32 v65, v66, v63
	v_fma_f32 v51, -v51, v65, v64
	v_div_fmas_f32 v51, v51, v63, v65
	v_div_fixup_f32 v63, v51, v50, 1.0
	v_div_scale_f32 v50, s[4:5], v49, v49, 1.0
	v_rcp_f32_e32 v51, v50
	s_nop 0
	v_fma_f32 v64, -v50, v51, 1.0
	v_fmac_f32_e32 v51, v64, v51
	v_div_scale_f32 v64, vcc, 1.0, v49, 1.0
	v_mul_f32_e32 v65, v64, v51
	v_fma_f32 v66, -v50, v65, v64
	v_fmac_f32_e32 v65, v66, v51
	v_fma_f32 v50, -v50, v65, v64
	v_div_fmas_f32 v50, v50, v51, v65
	v_div_fixup_f32 v64, v50, v49, 1.0
	v_div_scale_f32 v49, s[4:5], v48, v48, 1.0
	v_rcp_f32_e32 v50, v49
	s_nop 0
	v_fma_f32 v51, -v49, v50, 1.0
	v_fmac_f32_e32 v50, v51, v50
	v_div_scale_f32 v51, vcc, 1.0, v48, 1.0
	v_mul_f32_e32 v65, v51, v50
	v_fma_f32 v66, -v49, v65, v51
	v_fmac_f32_e32 v65, v66, v50
	v_fma_f32 v49, -v49, v65, v51
	v_div_fmas_f32 v49, v49, v50, v65
	v_sub_f32_e32 v51, v61, v47
	v_sub_f32_e32 v50, v60, v46
	v_pk_fma_f32 v[36:37], v[36:37], v[50:51], v[46:47]
	v_sub_f32_e32 v47, v81, v47
	v_sub_f32_e32 v46, v80, v46
	v_pk_fma_f32 v[36:37], v[40:41], v[46:47], v[36:37]
	v_div_fixup_f32 v65, v49, v48, 1.0
	v_mul_f32_e32 v36, 0xbfb8aa3b, v36
	v_mul_f32_e32 v37, 0xbfb8aa3b, v37
	v_exp_f32_e32 v36, v36
	v_exp_f32_e32 v37, v37
	v_sub_f32_e32 v49, v75, v45
	v_sub_f32_e32 v48, v74, v44
	v_pk_fma_f32 v[38:39], v[38:39], v[48:49], v[44:45]
	v_pk_add_f32 v[36:37], v[36:37], 1.0 op_sel_hi:[1,0]
	v_sub_f32_e32 v45, v83, v45
	v_div_scale_f32 v40, s[4:5], v37, v37, 1.0
	v_rcp_f32_e32 v41, v40
	v_sub_f32_e32 v44, v82, v44
	v_pk_fma_f32 v[38:39], v[42:43], v[44:45], v[38:39]
	v_fma_f32 v42, -v40, v41, 1.0
	v_fmac_f32_e32 v41, v42, v41
	v_div_scale_f32 v42, vcc, 1.0, v37, 1.0
	v_mul_f32_e32 v43, v42, v41
	v_fma_f32 v44, -v40, v43, v42
	v_fmac_f32_e32 v43, v44, v41
	v_fma_f32 v40, -v40, v43, v42
	v_div_fmas_f32 v40, v40, v41, v43
	v_div_fixup_f32 v40, v40, v37, 1.0
	v_div_scale_f32 v37, s[4:5], v36, v36, 1.0
	v_rcp_f32_e32 v41, v37
	s_nop 0
	v_fma_f32 v42, -v37, v41, 1.0
	v_fmac_f32_e32 v41, v42, v41
	v_div_scale_f32 v42, vcc, 1.0, v36, 1.0
	v_mul_f32_e32 v43, v42, v41
	v_fma_f32 v44, -v37, v43, v42
	v_fmac_f32_e32 v43, v44, v41
	v_fma_f32 v37, -v37, v43, v42
	v_div_fmas_f32 v37, v37, v41, v43
	v_div_fixup_f32 v41, v37, v36, 1.0
	v_mul_f32_e32 v36, 0xbfb8aa3b, v38
	v_mul_f32_e32 v37, 0xbfb8aa3b, v39
	v_exp_f32_e32 v36, v36
	v_exp_f32_e32 v37, v37
	s_nop 0
	v_pk_add_f32 v[36:37], v[36:37], 1.0 op_sel_hi:[1,0]
	s_nop 0
	v_div_scale_f32 v38, s[4:5], v37, v37, 1.0
	v_rcp_f32_e32 v39, v38
	s_nop 0
	v_fma_f32 v42, -v38, v39, 1.0
	v_fmac_f32_e32 v39, v42, v39
	v_div_scale_f32 v42, vcc, 1.0, v37, 1.0
	v_mul_f32_e32 v43, v42, v39
	v_fma_f32 v44, -v38, v43, v42
	v_fmac_f32_e32 v43, v44, v39
	v_fma_f32 v38, -v38, v43, v42
	v_div_fmas_f32 v38, v38, v39, v43
	v_div_fixup_f32 v39, v38, v37, 1.0
	v_div_scale_f32 v37, s[4:5], v36, v36, 1.0
	v_rcp_f32_e32 v38, v37
	s_nop 0
	v_fma_f32 v42, -v37, v38, 1.0
	v_fmac_f32_e32 v38, v42, v38
	v_div_scale_f32 v42, vcc, 1.0, v36, 1.0
	v_mul_f32_e32 v43, v42, v38
	v_fma_f32 v44, -v37, v43, v42
	v_fmac_f32_e32 v43, v44, v38
	v_fma_f32 v37, -v37, v43, v42
	v_div_fmas_f32 v37, v37, v38, v43
	v_div_fixup_f32 v42, v37, v36, 1.0
	v_cvt_pk_bf16_f32 v36, v63, v62
	v_cvt_pk_bf16_f32 v37, v65, v64
	v_cvt_pk_bf16_f32 v38, v41, v40
	v_cvt_pk_bf16_f32 v39, v42, v39
	global_load_dwordx4 v[40:43], v[54:55], off offset:128
	s_waitcnt vmcnt(0)
	v_lshlrev_b32_e32 v62, 16, v40
	v_and_b32_e32 v63, 0xffff0000, v40
	v_lshlrev_b32_e32 v60, 16, v41
	v_and_b32_e32 v61, 0xffff0000, v41
	v_lshlrev_b32_e32 v50, 16, v42
	v_and_b32_e32 v51, 0xffff0000, v42
	v_lshlrev_b32_e32 v48, 16, v43
	v_and_b32_e32 v49, 0xffff0000, v43
	global_load_dwordx4 v[40:43], v[52:53], off offset:128
	s_waitcnt vmcnt(0)
	v_cndmask_b32_e64 v43, v43, 0, s[38:39]
	v_cndmask_b32_e64 v42, v42, 0, s[38:39]
	v_cndmask_b32_e64 v41, v41, 0, s[38:39]
	v_cndmask_b32_e64 v40, v40, 0, s[38:39]
	v_lshlrev_b32_e32 v76, 16, v40
	v_and_b32_e32 v77, 0xffff0000, v40
	v_lshlrev_b32_e32 v74, 16, v41
	v_and_b32_e32 v75, 0xffff0000, v41
	v_lshlrev_b32_e32 v64, 16, v42
	v_and_b32_e32 v65, 0xffff0000, v42
	v_lshlrev_b32_e32 v78, 16, v43
	v_and_b32_e32 v79, 0xffff0000, v43
	global_load_dwordx4 v[40:43], v[58:59], off offset:128
	v_sub_f32_e32 v77, v77, v63
	v_sub_f32_e32 v76, v76, v62
	v_sub_f32_e32 v75, v75, v61
	v_sub_f32_e32 v74, v74, v60
	s_waitcnt vmcnt(0)
	v_cndmask_b32_e64 v43, v43, 0, s[36:37]
	v_cndmask_b32_e64 v42, v42, 0, s[36:37]
	v_cndmask_b32_e64 v41, v41, 0, s[36:37]
	v_cndmask_b32_e64 v40, v40, 0, s[36:37]
	v_lshlrev_b32_e32 v80, 16, v40
	v_and_b32_e32 v81, 0xffff0000, v40
	v_lshlrev_b32_e32 v82, 16, v41
	v_and_b32_e32 v83, 0xffff0000, v41
	v_lshlrev_b32_e32 v84, 16, v42
	v_and_b32_e32 v85, 0xffff0000, v42
	v_lshlrev_b32_e32 v86, 16, v43
	v_and_b32_e32 v87, 0xffff0000, v43
	global_load_dwordx4 v[40:43], v[176:177], off offset:272
	global_load_dwordx4 v[66:69], v[176:177], off offset:256
	global_load_dwordx4 v[44:47], v[176:177], off offset:912
	global_load_dwordx4 v[70:73], v[176:177], off offset:896
	s_waitcnt vmcnt(2)
	v_pk_fma_f32 v[66:67], v[66:67], v[76:77], v[62:63]
	v_sub_f32_e32 v63, v81, v63
	v_sub_f32_e32 v62, v80, v62
	s_waitcnt vmcnt(0)
	v_pk_fma_f32 v[62:63], v[70:71], v[62:63], v[66:67]
	v_pk_fma_f32 v[68:69], v[68:69], v[74:75], v[60:61]
	v_mul_f32_e32 v62, 0xbfb8aa3b, v62
	v_mul_f32_e32 v63, 0xbfb8aa3b, v63
	v_exp_f32_e32 v62, v62
	v_exp_f32_e32 v63, v63
	v_sub_f32_e32 v61, v83, v61
	v_sub_f32_e32 v60, v82, v60
	v_pk_fma_f32 v[60:61], v[72:73], v[60:61], v[68:69]
	v_pk_add_f32 v[62:63], v[62:63], 1.0 op_sel_hi:[1,0]
	v_mul_f32_e32 v60, 0xbfb8aa3b, v60
	v_div_scale_f32 v66, s[4:5], v63, v63, 1.0
	v_rcp_f32_e32 v67, v66
	v_mul_f32_e32 v61, 0xbfb8aa3b, v61
	v_exp_f32_e32 v60, v60
	v_exp_f32_e32 v61, v61
	v_fma_f32 v68, -v66, v67, 1.0
	v_fmac_f32_e32 v67, v68, v67
	v_div_scale_f32 v68, vcc, 1.0, v63, 1.0
	v_mul_f32_e32 v69, v68, v67
	v_fma_f32 v70, -v66, v69, v68
	v_fmac_f32_e32 v69, v70, v67
	v_fma_f32 v66, -v66, v69, v68
	v_div_fmas_f32 v66, v66, v67, v69
	v_div_fixup_f32 v66, v66, v63, 1.0
	v_div_scale_f32 v63, s[4:5], v62, v62, 1.0
	v_rcp_f32_e32 v67, v63
	v_pk_add_f32 v[60:61], v[60:61], 1.0 op_sel_hi:[1,0]
	v_fma_f32 v68, -v63, v67, 1.0
	v_fmac_f32_e32 v67, v68, v67
	v_div_scale_f32 v68, vcc, 1.0, v62, 1.0
	v_mul_f32_e32 v69, v68, v67
	v_fma_f32 v70, -v63, v69, v68
	v_fmac_f32_e32 v69, v70, v67
	v_fma_f32 v63, -v63, v69, v68
	v_div_fmas_f32 v63, v63, v67, v69
	v_div_fixup_f32 v67, v63, v62, 1.0
	v_div_scale_f32 v62, s[4:5], v61, v61, 1.0
	v_rcp_f32_e32 v63, v62
	s_nop 0
	v_fma_f32 v68, -v62, v63, 1.0
	v_fmac_f32_e32 v63, v68, v63
	v_div_scale_f32 v68, vcc, 1.0, v61, 1.0
	v_mul_f32_e32 v69, v68, v63
	v_fma_f32 v70, -v62, v69, v68
	v_fmac_f32_e32 v69, v70, v63
	v_fma_f32 v62, -v62, v69, v68
	v_div_fmas_f32 v62, v62, v63, v69
	v_div_fixup_f32 v68, v62, v61, 1.0
	v_div_scale_f32 v61, s[4:5], v60, v60, 1.0
	v_rcp_f32_e32 v62, v61
	s_nop 0
	v_fma_f32 v63, -v61, v62, 1.0
	v_fmac_f32_e32 v62, v63, v62
	v_div_scale_f32 v63, vcc, 1.0, v60, 1.0
	v_mul_f32_e32 v69, v63, v62
	v_fma_f32 v70, -v61, v69, v63
	v_fmac_f32_e32 v69, v70, v62
	v_fma_f32 v61, -v61, v69, v63
	v_div_fmas_f32 v61, v61, v62, v69
	v_sub_f32_e32 v63, v65, v51
	v_sub_f32_e32 v62, v64, v50
	v_pk_fma_f32 v[40:41], v[40:41], v[62:63], v[50:51]
	v_sub_f32_e32 v51, v85, v51
	v_sub_f32_e32 v50, v84, v50
	v_pk_fma_f32 v[40:41], v[44:45], v[50:51], v[40:41]
	v_div_fixup_f32 v69, v61, v60, 1.0
	v_mul_f32_e32 v40, 0xbfb8aa3b, v40
	v_mul_f32_e32 v41, 0xbfb8aa3b, v41
	v_exp_f32_e32 v40, v40
	v_exp_f32_e32 v41, v41
	v_sub_f32_e32 v61, v79, v49
	v_sub_f32_e32 v60, v78, v48
	v_pk_fma_f32 v[42:43], v[42:43], v[60:61], v[48:49]
	v_pk_add_f32 v[40:41], v[40:41], 1.0 op_sel_hi:[1,0]
	v_sub_f32_e32 v49, v87, v49
	v_div_scale_f32 v44, s[4:5], v41, v41, 1.0
	v_rcp_f32_e32 v45, v44
	v_sub_f32_e32 v48, v86, v48
	v_pk_fma_f32 v[42:43], v[46:47], v[48:49], v[42:43]
	v_fma_f32 v46, -v44, v45, 1.0
	v_fmac_f32_e32 v45, v46, v45
	v_div_scale_f32 v46, vcc, 1.0, v41, 1.0
	v_mul_f32_e32 v47, v46, v45
	v_fma_f32 v48, -v44, v47, v46
	v_fmac_f32_e32 v47, v48, v45
	v_fma_f32 v44, -v44, v47, v46
	v_div_fmas_f32 v44, v44, v45, v47
	v_div_fixup_f32 v44, v44, v41, 1.0
	v_div_scale_f32 v41, s[4:5], v40, v40, 1.0
	v_rcp_f32_e32 v45, v41
	s_nop 0
	v_fma_f32 v46, -v41, v45, 1.0
	v_fmac_f32_e32 v45, v46, v45
	v_div_scale_f32 v46, vcc, 1.0, v40, 1.0
	v_mul_f32_e32 v47, v46, v45
	v_fma_f32 v48, -v41, v47, v46
	v_fmac_f32_e32 v47, v48, v45
	v_fma_f32 v41, -v41, v47, v46
	v_div_fmas_f32 v41, v41, v45, v47
	v_div_fixup_f32 v45, v41, v40, 1.0
	v_mul_f32_e32 v40, 0xbfb8aa3b, v42
	v_mul_f32_e32 v41, 0xbfb8aa3b, v43
	v_exp_f32_e32 v40, v40
	v_exp_f32_e32 v41, v41
	s_nop 0
	v_pk_add_f32 v[40:41], v[40:41], 1.0 op_sel_hi:[1,0]
	s_nop 0
	v_div_scale_f32 v42, s[4:5], v41, v41, 1.0
	v_rcp_f32_e32 v43, v42
	s_nop 0
	v_fma_f32 v46, -v42, v43, 1.0
	v_fmac_f32_e32 v43, v46, v43
	v_div_scale_f32 v46, vcc, 1.0, v41, 1.0
	v_mul_f32_e32 v47, v46, v43
	v_fma_f32 v48, -v42, v47, v46
	v_fmac_f32_e32 v47, v48, v43
	v_fma_f32 v42, -v42, v47, v46
	v_div_fmas_f32 v42, v42, v43, v47
	v_div_fixup_f32 v43, v42, v41, 1.0
	v_div_scale_f32 v41, s[4:5], v40, v40, 1.0
	v_rcp_f32_e32 v42, v41
	s_nop 0
	v_fma_f32 v46, -v41, v42, 1.0
	v_fmac_f32_e32 v42, v46, v42
	v_div_scale_f32 v46, vcc, 1.0, v40, 1.0
	v_mul_f32_e32 v47, v46, v42
	v_fma_f32 v48, -v41, v47, v46
	v_fmac_f32_e32 v47, v48, v42
	v_fma_f32 v41, -v41, v47, v46
	v_div_fmas_f32 v41, v41, v42, v47
	v_div_fixup_f32 v46, v41, v40, 1.0
	v_cvt_pk_bf16_f32 v40, v67, v66
	v_cvt_pk_bf16_f32 v41, v69, v68
	v_cvt_pk_bf16_f32 v42, v45, v44
	v_cvt_pk_bf16_f32 v43, v46, v43
	global_load_dwordx4 v[44:47], v[54:55], off offset:192
	s_waitcnt vmcnt(0)
	v_lshlrev_b32_e32 v66, 16, v44
	v_and_b32_e32 v67, 0xffff0000, v44
	v_lshlrev_b32_e32 v64, 16, v45
	v_and_b32_e32 v65, 0xffff0000, v45
	v_lshlrev_b32_e32 v62, 16, v46
	v_and_b32_e32 v63, 0xffff0000, v46
	v_lshlrev_b32_e32 v60, 16, v47
	v_and_b32_e32 v61, 0xffff0000, v47
	global_load_dwordx4 v[44:47], v[52:53], off offset:192
	s_waitcnt vmcnt(0)
	v_cndmask_b32_e64 v47, v47, 0, s[38:39]
	v_cndmask_b32_e64 v46, v46, 0, s[38:39]
	v_cndmask_b32_e64 v45, v45, 0, s[38:39]
	v_cndmask_b32_e64 v44, v44, 0, s[38:39]
	v_lshlrev_b32_e32 v80, 16, v44
	v_and_b32_e32 v81, 0xffff0000, v44
	v_lshlrev_b32_e32 v78, 16, v45
	v_and_b32_e32 v79, 0xffff0000, v45
	v_lshlrev_b32_e32 v68, 16, v46
	v_and_b32_e32 v69, 0xffff0000, v46
	v_lshlrev_b32_e32 v82, 16, v47
	v_and_b32_e32 v83, 0xffff0000, v47
	global_load_dwordx4 v[44:47], v[58:59], off offset:192
	v_sub_f32_e32 v81, v81, v67
	v_sub_f32_e32 v80, v80, v66
	v_sub_f32_e32 v79, v79, v65
	v_sub_f32_e32 v78, v78, v64
	s_waitcnt vmcnt(0)
	v_cndmask_b32_e64 v47, v47, 0, s[36:37]
	v_cndmask_b32_e64 v46, v46, 0, s[36:37]
	v_cndmask_b32_e64 v45, v45, 0, s[36:37]
	v_cndmask_b32_e64 v44, v44, 0, s[36:37]
	v_lshlrev_b32_e32 v84, 16, v44
	v_and_b32_e32 v85, 0xffff0000, v44
	v_lshlrev_b32_e32 v86, 16, v45
	v_and_b32_e32 v87, 0xffff0000, v45
	v_lshlrev_b32_e32 v88, 16, v46
	v_and_b32_e32 v89, 0xffff0000, v46
	v_lshlrev_b32_e32 v90, 16, v47
	v_and_b32_e32 v91, 0xffff0000, v47
	global_load_dwordx4 v[44:47], v[176:177], off offset:400
	global_load_dwordx4 v[70:73], v[176:177], off offset:384
	global_load_dwordx4 v[48:51], v[176:177], off offset:1040
	global_load_dwordx4 v[74:77], v[176:177], off offset:1024
	s_waitcnt vmcnt(2)
	v_pk_fma_f32 v[70:71], v[70:71], v[80:81], v[66:67]
	v_sub_f32_e32 v67, v85, v67
	v_sub_f32_e32 v66, v84, v66
	s_waitcnt vmcnt(0)
	v_pk_fma_f32 v[66:67], v[74:75], v[66:67], v[70:71]
	v_pk_fma_f32 v[72:73], v[72:73], v[78:79], v[64:65]
	v_mul_f32_e32 v66, 0xbfb8aa3b, v66
	v_mul_f32_e32 v67, 0xbfb8aa3b, v67
	v_exp_f32_e32 v66, v66
	v_exp_f32_e32 v67, v67
	v_sub_f32_e32 v65, v87, v65
	v_sub_f32_e32 v64, v86, v64
	v_pk_fma_f32 v[64:65], v[76:77], v[64:65], v[72:73]
	v_pk_add_f32 v[66:67], v[66:67], 1.0 op_sel_hi:[1,0]
	v_mul_f32_e32 v64, 0xbfb8aa3b, v64
	v_div_scale_f32 v70, s[4:5], v67, v67, 1.0
	v_rcp_f32_e32 v71, v70
	v_mul_f32_e32 v65, 0xbfb8aa3b, v65
	v_exp_f32_e32 v64, v64
	v_exp_f32_e32 v65, v65
	v_fma_f32 v72, -v70, v71, 1.0
	v_fmac_f32_e32 v71, v72, v71
	v_div_scale_f32 v72, vcc, 1.0, v67, 1.0
	v_mul_f32_e32 v73, v72, v71
	v_fma_f32 v74, -v70, v73, v72
	v_fmac_f32_e32 v73, v74, v71
	v_fma_f32 v70, -v70, v73, v72
	v_div_fmas_f32 v70, v70, v71, v73
	v_div_fixup_f32 v70, v70, v67, 1.0
	v_div_scale_f32 v67, s[4:5], v66, v66, 1.0
	v_rcp_f32_e32 v71, v67
	v_pk_add_f32 v[64:65], v[64:65], 1.0 op_sel_hi:[1,0]
	v_fma_f32 v72, -v67, v71, 1.0
	v_fmac_f32_e32 v71, v72, v71
	v_div_scale_f32 v72, vcc, 1.0, v66, 1.0
	v_mul_f32_e32 v73, v72, v71
	v_fma_f32 v74, -v67, v73, v72
	v_fmac_f32_e32 v73, v74, v71
	v_fma_f32 v67, -v67, v73, v72
	v_div_fmas_f32 v67, v67, v71, v73
	v_div_fixup_f32 v71, v67, v66, 1.0
	v_div_scale_f32 v66, s[4:5], v65, v65, 1.0
	v_rcp_f32_e32 v67, v66
	s_nop 0
	v_fma_f32 v72, -v66, v67, 1.0
	v_fmac_f32_e32 v67, v72, v67
	v_div_scale_f32 v72, vcc, 1.0, v65, 1.0
	v_mul_f32_e32 v73, v72, v67
	v_fma_f32 v74, -v66, v73, v72
	v_fmac_f32_e32 v73, v74, v67
	v_fma_f32 v66, -v66, v73, v72
	v_div_fmas_f32 v66, v66, v67, v73
	v_div_fixup_f32 v72, v66, v65, 1.0
	v_div_scale_f32 v65, s[4:5], v64, v64, 1.0
	v_rcp_f32_e32 v66, v65
	s_nop 0
	v_fma_f32 v67, -v65, v66, 1.0
	v_fmac_f32_e32 v66, v67, v66
	v_div_scale_f32 v67, vcc, 1.0, v64, 1.0
	v_mul_f32_e32 v73, v67, v66
	v_fma_f32 v74, -v65, v73, v67
	v_fmac_f32_e32 v73, v74, v66
	v_fma_f32 v65, -v65, v73, v67
	v_div_fmas_f32 v65, v65, v66, v73
	v_sub_f32_e32 v67, v69, v63
	v_sub_f32_e32 v66, v68, v62
	v_pk_fma_f32 v[44:45], v[44:45], v[66:67], v[62:63]
	v_sub_f32_e32 v63, v89, v63
	v_sub_f32_e32 v62, v88, v62
	v_pk_fma_f32 v[44:45], v[48:49], v[62:63], v[44:45]
	v_div_fixup_f32 v73, v65, v64, 1.0
	v_mul_f32_e32 v44, 0xbfb8aa3b, v44
	v_mul_f32_e32 v45, 0xbfb8aa3b, v45
	v_exp_f32_e32 v44, v44
	v_exp_f32_e32 v45, v45
	v_sub_f32_e32 v65, v83, v61
	v_sub_f32_e32 v64, v82, v60
	v_pk_fma_f32 v[46:47], v[46:47], v[64:65], v[60:61]
	v_pk_add_f32 v[44:45], v[44:45], 1.0 op_sel_hi:[1,0]
	v_sub_f32_e32 v61, v91, v61
	v_div_scale_f32 v48, s[4:5], v45, v45, 1.0
	v_rcp_f32_e32 v49, v48
	v_sub_f32_e32 v60, v90, v60
	v_pk_fma_f32 v[46:47], v[50:51], v[60:61], v[46:47]
	v_fma_f32 v50, -v48, v49, 1.0
	v_fmac_f32_e32 v49, v50, v49
	v_div_scale_f32 v50, vcc, 1.0, v45, 1.0
	v_mul_f32_e32 v51, v50, v49
	v_fma_f32 v60, -v48, v51, v50
	v_fmac_f32_e32 v51, v60, v49
	v_fma_f32 v48, -v48, v51, v50
	v_div_fmas_f32 v48, v48, v49, v51
	v_div_fixup_f32 v48, v48, v45, 1.0
	v_div_scale_f32 v45, s[4:5], v44, v44, 1.0
	v_rcp_f32_e32 v49, v45
	s_nop 0
	v_fma_f32 v50, -v45, v49, 1.0
	v_fmac_f32_e32 v49, v50, v49
	v_div_scale_f32 v50, vcc, 1.0, v44, 1.0
	v_mul_f32_e32 v51, v50, v49
	v_fma_f32 v60, -v45, v51, v50
	v_fmac_f32_e32 v51, v60, v49
	v_fma_f32 v45, -v45, v51, v50
	v_div_fmas_f32 v45, v45, v49, v51
	v_div_fixup_f32 v49, v45, v44, 1.0
	v_mul_f32_e32 v44, 0xbfb8aa3b, v46
	v_mul_f32_e32 v45, 0xbfb8aa3b, v47
	v_exp_f32_e32 v44, v44
	v_exp_f32_e32 v45, v45
	s_nop 0
	v_pk_add_f32 v[44:45], v[44:45], 1.0 op_sel_hi:[1,0]
	s_nop 0
	v_div_scale_f32 v46, s[4:5], v45, v45, 1.0
	v_rcp_f32_e32 v47, v46
	s_nop 0
	v_fma_f32 v50, -v46, v47, 1.0
	v_fmac_f32_e32 v47, v50, v47
	v_div_scale_f32 v50, vcc, 1.0, v45, 1.0
	v_mul_f32_e32 v51, v50, v47
	v_fma_f32 v60, -v46, v51, v50
	v_fmac_f32_e32 v51, v60, v47
	v_fma_f32 v46, -v46, v51, v50
	v_div_fmas_f32 v46, v46, v47, v51
	v_div_fixup_f32 v47, v46, v45, 1.0
	v_div_scale_f32 v45, s[4:5], v44, v44, 1.0
	v_rcp_f32_e32 v46, v45
	s_nop 0
	v_fma_f32 v50, -v45, v46, 1.0
	v_fmac_f32_e32 v46, v50, v46
	v_div_scale_f32 v50, vcc, 1.0, v44, 1.0
	v_mul_f32_e32 v51, v50, v46
	v_fma_f32 v60, -v45, v51, v50
	v_fmac_f32_e32 v51, v60, v46
	v_fma_f32 v45, -v45, v51, v50
	v_div_fmas_f32 v45, v45, v46, v51
	v_div_fixup_f32 v50, v45, v44, 1.0
	v_cvt_pk_bf16_f32 v44, v71, v70
	v_cvt_pk_bf16_f32 v45, v73, v72
	v_cvt_pk_bf16_f32 v46, v49, v48
	v_cvt_pk_bf16_f32 v47, v50, v47
	global_load_dwordx4 v[48:51], v[54:55], off offset:256
	s_waitcnt vmcnt(0)
	v_lshlrev_b32_e32 v66, 16, v48
	v_and_b32_e32 v67, 0xffff0000, v48
	v_lshlrev_b32_e32 v64, 16, v49
	v_and_b32_e32 v65, 0xffff0000, v49
	v_lshlrev_b32_e32 v62, 16, v50
	v_and_b32_e32 v63, 0xffff0000, v50
	v_lshlrev_b32_e32 v60, 16, v51
	v_and_b32_e32 v61, 0xffff0000, v51
	global_load_dwordx4 v[48:51], v[52:53], off offset:256
	s_waitcnt vmcnt(0)
	v_cndmask_b32_e64 v51, v51, 0, s[38:39]
	v_cndmask_b32_e64 v50, v50, 0, s[38:39]
	v_cndmask_b32_e64 v49, v49, 0, s[38:39]
	v_cndmask_b32_e64 v48, v48, 0, s[38:39]
	v_lshlrev_b32_e32 v78, 16, v48
	v_and_b32_e32 v79, 0xffff0000, v48
	v_lshlrev_b32_e32 v80, 16, v49
	v_and_b32_e32 v81, 0xffff0000, v49
	v_lshlrev_b32_e32 v68, 16, v50
	v_and_b32_e32 v69, 0xffff0000, v50
	v_lshlrev_b32_e32 v82, 16, v51
	v_and_b32_e32 v83, 0xffff0000, v51
	global_load_dwordx4 v[48:51], v[58:59], off offset:256
	v_sub_f32_e32 v59, v81, v65
	v_sub_f32_e32 v58, v80, v64
	v_sub_f32_e32 v79, v79, v67
	v_sub_f32_e32 v78, v78, v66
	s_waitcnt vmcnt(0)
	v_cndmask_b32_e64 v51, v51, 0, s[36:37]
	v_cndmask_b32_e64 v50, v50, 0, s[36:37]
	v_cndmask_b32_e64 v49, v49, 0, s[36:37]
	v_cndmask_b32_e64 v48, v48, 0, s[36:37]
	v_lshlrev_b32_e32 v84, 16, v48
	v_and_b32_e32 v85, 0xffff0000, v48
	v_lshlrev_b32_e32 v86, 16, v49
	v_and_b32_e32 v87, 0xffff0000, v49
	v_lshlrev_b32_e32 v88, 16, v50
	v_and_b32_e32 v89, 0xffff0000, v50
	v_lshlrev_b32_e32 v90, 16, v51
	v_and_b32_e32 v91, 0xffff0000, v51
	global_load_dwordx4 v[48:51], v[176:177], off offset:528
	global_load_dwordx4 v[70:73], v[176:177], off offset:512
	global_load_dwordx4 v[52:55], v[176:177], off offset:1168
	global_load_dwordx4 v[74:77], v[176:177], off offset:1152
	s_waitcnt vmcnt(2)
	v_pk_fma_f32 v[70:71], v[70:71], v[78:79], v[66:67]
	v_pk_fma_f32 v[58:59], v[72:73], v[58:59], v[64:65]
	v_sub_f32_e32 v67, v85, v67
	v_sub_f32_e32 v66, v84, v66
	v_sub_f32_e32 v65, v87, v65
	v_sub_f32_e32 v64, v86, v64
	s_waitcnt vmcnt(0)
	v_pk_fma_f32 v[58:59], v[76:77], v[64:65], v[58:59]
	v_pk_fma_f32 v[64:65], v[74:75], v[66:67], v[70:71]
	v_mul_f32_e32 v58, 0xbfb8aa3b, v58
	v_mul_f32_e32 v64, 0xbfb8aa3b, v64
	v_mul_f32_e32 v65, 0xbfb8aa3b, v65
	v_exp_f32_e32 v64, v64
	v_exp_f32_e32 v65, v65
	v_mul_f32_e32 v59, 0xbfb8aa3b, v59
	v_exp_f32_e32 v58, v58
	v_exp_f32_e32 v59, v59
	v_pk_add_f32 v[64:65], v[64:65], 1.0 op_sel_hi:[1,0]
	v_pk_add_f32 v[58:59], v[58:59], 1.0 op_sel_hi:[1,0]
	v_div_scale_f32 v66, s[4:5], v65, v65, 1.0
	v_rcp_f32_e32 v67, v66
	s_nop 0
	v_fma_f32 v70, -v66, v67, 1.0
	v_fmac_f32_e32 v67, v70, v67
	v_div_scale_f32 v70, vcc, 1.0, v65, 1.0
	v_mul_f32_e32 v71, v70, v67
	v_fma_f32 v72, -v66, v71, v70
	v_fmac_f32_e32 v71, v72, v67
	v_fma_f32 v66, -v66, v71, v70
	v_div_fmas_f32 v66, v66, v67, v71
	v_div_fixup_f32 v66, v66, v65, 1.0
	v_div_scale_f32 v65, s[4:5], v64, v64, 1.0
	v_rcp_f32_e32 v67, v65
	s_nop 0
	v_fma_f32 v70, -v65, v67, 1.0
	v_fmac_f32_e32 v67, v70, v67
	v_div_scale_f32 v70, vcc, 1.0, v64, 1.0
	v_mul_f32_e32 v71, v70, v67
	v_fma_f32 v72, -v65, v71, v70
	v_fmac_f32_e32 v71, v72, v67
	v_fma_f32 v65, -v65, v71, v70
	v_div_fmas_f32 v65, v65, v67, v71
	v_div_fixup_f32 v67, v65, v64, 1.0
	v_div_scale_f32 v64, s[4:5], v59, v59, 1.0
	v_rcp_f32_e32 v65, v64
	s_nop 0
	v_fma_f32 v70, -v64, v65, 1.0
	v_fmac_f32_e32 v65, v70, v65
	v_div_scale_f32 v70, vcc, 1.0, v59, 1.0
	v_mul_f32_e32 v71, v70, v65
	v_fma_f32 v72, -v64, v71, v70
	v_fmac_f32_e32 v71, v72, v65
	v_fma_f32 v64, -v64, v71, v70
	v_div_fmas_f32 v64, v64, v65, v71
	v_div_fixup_f32 v70, v64, v59, 1.0
	v_div_scale_f32 v59, s[4:5], v58, v58, 1.0
	v_rcp_f32_e32 v64, v59
	s_nop 0
	v_fma_f32 v65, -v59, v64, 1.0
	v_fmac_f32_e32 v64, v65, v64
	v_div_scale_f32 v65, vcc, 1.0, v58, 1.0
	v_mul_f32_e32 v71, v65, v64
	v_fma_f32 v72, -v59, v71, v65
	v_fmac_f32_e32 v71, v72, v64
	v_fma_f32 v59, -v59, v71, v65
	v_div_fmas_f32 v59, v59, v64, v71
	v_div_fixup_f32 v71, v59, v58, 1.0
	v_sub_f32_e32 v59, v83, v61
	v_sub_f32_e32 v58, v82, v60
	v_sub_f32_e32 v65, v69, v63
	v_sub_f32_e32 v64, v68, v62
	v_pk_fma_f32 v[48:49], v[48:49], v[64:65], v[62:63]
	v_pk_fma_f32 v[50:51], v[50:51], v[58:59], v[60:61]
	v_sub_f32_e32 v59, v89, v63
	v_sub_f32_e32 v58, v88, v62
	v_pk_fma_f32 v[48:49], v[52:53], v[58:59], v[48:49]
	v_sub_f32_e32 v61, v91, v61
	v_mul_f32_e32 v48, 0xbfb8aa3b, v48
	v_mul_f32_e32 v49, 0xbfb8aa3b, v49
	v_exp_f32_e32 v48, v48
	v_exp_f32_e32 v49, v49
	v_sub_f32_e32 v60, v90, v60
	v_pk_fma_f32 v[50:51], v[54:55], v[60:61], v[50:51]
	v_pk_add_f32 v[48:49], v[48:49], 1.0 op_sel_hi:[1,0]
	s_nop 0
	v_div_scale_f32 v52, s[4:5], v49, v49, 1.0
	v_rcp_f32_e32 v53, v52
	s_nop 0
	v_fma_f32 v54, -v52, v53, 1.0
	v_fmac_f32_e32 v53, v54, v53
	v_div_scale_f32 v54, vcc, 1.0, v49, 1.0
	v_mul_f32_e32 v55, v54, v53
	v_fma_f32 v58, -v52, v55, v54
	v_fmac_f32_e32 v55, v58, v53
	v_fma_f32 v52, -v52, v55, v54
	v_div_fmas_f32 v52, v52, v53, v55
	v_div_fixup_f32 v52, v52, v49, 1.0
	v_div_scale_f32 v49, s[4:5], v48, v48, 1.0
	v_rcp_f32_e32 v53, v49
	s_nop 0
	v_fma_f32 v54, -v49, v53, 1.0
	v_fmac_f32_e32 v53, v54, v53
	v_div_scale_f32 v54, vcc, 1.0, v48, 1.0
	v_mul_f32_e32 v55, v54, v53
	v_fma_f32 v58, -v49, v55, v54
	v_fmac_f32_e32 v55, v58, v53
	v_fma_f32 v49, -v49, v55, v54
	v_div_fmas_f32 v49, v49, v53, v55
	v_div_fixup_f32 v53, v49, v48, 1.0
	v_mul_f32_e32 v48, 0xbfb8aa3b, v50
	v_mul_f32_e32 v49, 0xbfb8aa3b, v51
	v_exp_f32_e32 v48, v48
	v_exp_f32_e32 v49, v49
	s_nop 0
	v_pk_add_f32 v[48:49], v[48:49], 1.0 op_sel_hi:[1,0]
	s_nop 0
	v_div_scale_f32 v50, s[4:5], v49, v49, 1.0
	v_rcp_f32_e32 v51, v50
	s_nop 0
	v_fma_f32 v54, -v50, v51, 1.0
	v_fmac_f32_e32 v51, v54, v51
	v_div_scale_f32 v54, vcc, 1.0, v49, 1.0
	v_mul_f32_e32 v55, v54, v51
	v_fma_f32 v58, -v50, v55, v54
	v_fmac_f32_e32 v55, v58, v51
	v_fma_f32 v50, -v50, v55, v54
	v_div_fmas_f32 v50, v50, v51, v55
	v_div_fixup_f32 v51, v50, v49, 1.0
	v_div_scale_f32 v49, s[4:5], v48, v48, 1.0
	v_rcp_f32_e32 v50, v49
	s_lshl_b32 s4, s10, 6
	s_or_b32 s6, s2, s4
	v_add_u32_e32 v190, s6, v164
	v_fma_f32 v54, -v49, v50, 1.0
	v_fmac_f32_e32 v50, v54, v50
	v_div_scale_f32 v54, vcc, 1.0, v48, 1.0
	v_mul_f32_e32 v55, v54, v50
	v_fma_f32 v58, -v49, v55, v54
	v_fmac_f32_e32 v55, v58, v50
	v_fma_f32 v49, -v49, v55, v54
	v_div_fmas_f32 v49, v49, v50, v55
	v_div_fixup_f32 v54, v49, v48, 1.0
	v_or_b32_e32 v58, s6, v227
	v_cvt_pk_bf16_f32 v48, v67, v66
	v_cvt_pk_bf16_f32 v49, v71, v70
	v_cvt_pk_bf16_f32 v50, v53, v52
	v_cvt_pk_bf16_f32 v51, v54, v51
	v_lshlrev_b32_e32 v208, 7, v58
	v_ashrrev_i32_e32 v191, 31, v190
	v_lshl_add_u64 v[54:55], v[168:169], 0, v[208:209]
	v_lshl_add_u64 v[52:53], v[190:191], 2, s[42:43]
	global_load_dwordx4 v[76:79], v[54:55], off
	global_load_dwordx4 v[80:83], v[54:55], off offset:64
	global_load_dwordx4 v[68:71], v[52:53], off offset:48
	global_load_dwordx4 v[72:75], v[52:53], off offset:32
	global_load_dwordx4 v[84:87], v[52:53], off offset:16
	global_load_dwordx4 v[96:99], v[52:53], off
	global_load_dwordx4 v[88:91], v[54:55], off offset:512
	global_load_dwordx4 v[92:95], v[54:55], off offset:576
	global_load_dwordx4 v[100:103], v[54:55], off offset:1024
	global_load_dwordx4 v[104:107], v[54:55], off offset:1088
	global_load_dwordx4 v[108:111], v[54:55], off offset:1536
	global_load_dwordx4 v[112:115], v[54:55], off offset:1600
	v_lshlrev_b64 v[52:53], 11, v[56:57]
	v_lshl_add_u64 v[192:193], s[52:53], 0, v[52:53]
	v_lshl_add_u64 v[52:53], v[178:179], 0, v[52:53]
	s_lshl_b32 s24, s6, 1
	v_lshl_add_u64 v[194:195], v[52:53], 0, s[24:25]
	v_or_b32_e32 v52, s6, v228
	v_lshl_add_u64 v[198:199], v[180:181], 0, v[208:209]
	v_lshlrev_b32_e32 v208, 7, v52
	v_lshl_add_u64 v[204:205], v[180:181], 0, v[208:209]
	v_mul_u32_u24_e32 v208, 0x140, v52
	v_or_b32_e32 v52, s6, v229
	v_lshl_add_u64 v[206:207], v[184:185], 0, v[208:209]
	v_mul_u32_u24_e32 v208, 0x140, v52
	v_or_b32_e32 v53, s6, v230
	v_lshl_add_u64 v[216:217], v[184:185], 0, v[208:209]
	v_lshlrev_b32_e32 v208, 7, v53
	v_lshl_add_u64 v[218:219], v[180:181], 0, v[208:209]
	v_mul_u32_u24_e32 v208, 0x140, v53
	v_add_lshl_u32 v196, s6, v165, 7
	s_movk_i32 s4, 0x140
	v_lshl_add_u64 v[220:221], v[184:185], 0, v[208:209]
	v_lshlrev_b32_e32 v208, 7, v52
	v_lshl_add_u64 v[200:201], v[182:183], 0, v[196:197]
	v_mad_u64_u32 v[202:203], s[4:5], v58, s4, v[184:185]
	v_lshl_add_u64 v[222:223], v[180:181], 0, v[208:209]
